# epilogue de-serialisation: 12 in-proj epi_store64 ladders + outproj residual ladder issue all ds_read_b128 up front into pool regs, counted lgkmcnt
# speedup vs baseline: 1.0064x; 1.0064x over previous
; #define G_STORE(ST, S, unused) do { char* d_ = smem + (ST) * STAGE; \
;     *(uint4*)(d_ + alo[0]) = S##a0; *(uint4*)(d_ + alo[1]) = S##a1; *(uint4*)(d_ + alo[2]) = S##a2; *(uint4*)(d_ + alo[3]) = S##a3; \
;     *(uint4*)(d_ + blo[0]) = S##b0; *(uint4*)(d_ + blo[1]) = S##b1; \
;     if (NBCH == 4) { *(uint4*)(d_ + blo[NBCH - 2]) = S##b2; *(uint4*)(d_ + blo[NBCH - 1]) = S##b3; } } while (0)
; template <int NJ, class RowA>
; DI void gemm_main(f32x16 (&acc)[2][NJ], const bf16_t* __restrict__ A, RowA rowA, size_t kstrideA, int m0, int Mmax,
;                   const bf16_t* __restrict__ Bt, size_t ldb, int n0, int nk, char* smem) {
;     ...
;   __syncthreads();
;   G_LOAD(x0, 0, 0);
;   G_LOAD(x1, 0, 1);
;   G_STORE(0, x0, 0);
;   __syncthreads();
; #pragma unroll 1
;   for (int kt = 0; kt < nk; kt += 2) {
;     G_LOAD(x0, 0, (kt + 2 < nk ? kt + 2 : nk - 1));
;     G_COMPUTE(0);
;     G_STORE(1, x1, 0);
;     __syncthreads();
;     G_LOAD(x1, 0, (kt + 3 < nk ? kt + 3 : nk - 1));
;     G_COMPUTE(1);
;     G_STORE(0, x0, 0);
;     __syncthreads();
;   }
.Lpeel_tail_12:
	ds_read_b128 v[166:169], v0
	ds_read_b128 v[170:173], v139 offset:18432
	ds_read_b128 v[174:177], v139 offset:23040
	ds_read_b128 v[178:181], v0 offset:4608
	s_add_i32 s4, s3, 4
	s_min_u32 s4, s4, 15
	s_lshl_b32 s14, s4, 7
	v_lshl_add_u64 v[98:99], v[122:123], 0, s[14:15]
	v_lshl_add_u64 v[102:103], v[124:125], 0, s[14:15]
	v_lshl_add_u64 v[106:107], v[126:127], 0, s[14:15]
	v_lshl_add_u64 v[110:111], v[128:129], 0, s[14:15]
	v_lshl_add_u64 v[114:115], v[130:131], 0, s[14:15]
	v_lshl_add_u64 v[118:119], v[132:133], 0, s[14:15]
	s_add_i32 s3, s3, 2
	v_lshl_add_u64 v[158:159], v[134:135], 0, s[14:15]
	v_lshl_add_u64 v[160:161], v[136:137], 0, s[14:15]
	s_setprio 1
	ds_read_b128 v[182:185], v0 offset:32
	ds_read_b128 v[186:189], v139 offset:18464
	ds_read_b128 v[190:193], v139 offset:23072
	ds_read_b128 v[194:197], v0 offset:4640
	s_waitcnt lgkmcnt(4)
	v_mfma_f32_32x32x16_bf16 v[50:65], v[166:169], v[170:173], v[50:65]
	v_mfma_f32_32x32x16_bf16 v[34:49], v[166:169], v[174:177], v[34:49]
	v_mfma_f32_32x32x16_bf16 v[18:33], v[178:181], v[170:173], v[18:33]
	v_mfma_f32_32x32x16_bf16 v[2:17], v[178:181], v[174:177], v[2:17]
	ds_read_b128 v[166:169], v0 offset:64
	ds_read_b128 v[170:173], v139 offset:18496
	ds_read_b128 v[174:177], v139 offset:23104
	ds_read_b128 v[178:181], v0 offset:4672
	s_waitcnt lgkmcnt(4)
	v_mfma_f32_32x32x16_bf16 v[50:65], v[182:185], v[186:189], v[50:65]
	v_mfma_f32_32x32x16_bf16 v[34:49], v[182:185], v[190:193], v[34:49]
	v_mfma_f32_32x32x16_bf16 v[18:33], v[194:197], v[186:189], v[18:33]
	v_mfma_f32_32x32x16_bf16 v[2:17], v[194:197], v[190:193], v[2:17]
	ds_read_b128 v[182:185], v0 offset:96
	ds_read_b128 v[186:189], v139 offset:18528
	ds_read_b128 v[190:193], v139 offset:23136
	ds_read_b128 v[194:197], v0 offset:4704
	s_waitcnt lgkmcnt(4)
	v_mfma_f32_32x32x16_bf16 v[50:65], v[166:169], v[170:173], v[50:65]
	s_waitcnt vmcnt(0)
	ds_write_b128 v138, v[78:81] offset:36864
	v_mfma_f32_32x32x16_bf16 v[34:49], v[166:169], v[174:177], v[34:49]
	ds_write_b128 v140, v[86:89] offset:36864
	v_mfma_f32_32x32x16_bf16 v[18:33], v[178:181], v[170:173], v[18:33]
	ds_write_b128 v142, v[90:93] offset:36864
	v_mfma_f32_32x32x16_bf16 v[2:17], v[178:181], v[174:177], v[2:17]
	ds_write_b128 v144, v[94:97] offset:36864
	s_waitcnt lgkmcnt(4)
	v_mfma_f32_32x32x16_bf16 v[50:65], v[182:185], v[186:189], v[50:65]
	ds_write_b128 v138, v[74:77] offset:55296
	v_mfma_f32_32x32x16_bf16 v[34:49], v[182:185], v[190:193], v[34:49]
	ds_write_b128 v140, v[82:85] offset:55296
	v_mfma_f32_32x32x16_bf16 v[18:33], v[194:197], v[186:189], v[18:33]
	ds_write_b128 v142, v[66:69] offset:55296
	v_mfma_f32_32x32x16_bf16 v[2:17], v[194:197], v[190:193], v[2:17]
	ds_write_b128 v144, v[70:73] offset:55296
	s_setprio 0
	s_min_u32 s4, s3, 12
	s_lshl_b32 s14, s4, 7
	v_lshl_add_u64 v[66:67], v[122:123], 0, s[14:15]
	v_lshl_add_u64 v[68:69], v[124:125], 0, s[14:15]
	v_lshl_add_u64 v[70:71], v[126:127], 0, s[14:15]
	v_lshl_add_u64 v[72:73], v[128:129], 0, s[14:15]
	v_lshl_add_u64 v[74:75], v[130:131], 0, s[14:15]
	v_lshl_add_u64 v[82:83], v[132:133], 0, s[14:15]
	s_waitcnt lgkmcnt(0)
	s_barrier
	ds_read_b128 v[166:169], v0 offset:36864
	ds_read_b128 v[170:173], v139 offset:55296
	ds_read_b128 v[174:177], v139 offset:59904
	ds_read_b128 v[178:181], v0 offset:41472
	v_lshl_add_u64 v[154:155], v[134:135], 0, s[14:15]
	v_lshl_add_u64 v[156:157], v[136:137], 0, s[14:15]
	s_setprio 1
	ds_read_b128 v[182:185], v0 offset:36896
	ds_read_b128 v[186:189], v139 offset:55328
	ds_read_b128 v[190:193], v139 offset:59936
	ds_read_b128 v[194:197], v0 offset:41504
	s_waitcnt lgkmcnt(4)
	v_mfma_f32_32x32x16_bf16 v[50:65], v[166:169], v[170:173], v[50:65]
	v_mfma_f32_32x32x16_bf16 v[34:49], v[166:169], v[174:177], v[34:49]
	v_mfma_f32_32x32x16_bf16 v[18:33], v[178:181], v[170:173], v[18:33]
	v_mfma_f32_32x32x16_bf16 v[2:17], v[178:181], v[174:177], v[2:17]
	ds_read_b128 v[166:169], v0 offset:36928
	ds_read_b128 v[170:173], v139 offset:55360
	ds_read_b128 v[174:177], v139 offset:59968
	ds_read_b128 v[178:181], v0 offset:41536
	s_waitcnt lgkmcnt(4)
	v_mfma_f32_32x32x16_bf16 v[50:65], v[182:185], v[186:189], v[50:65]
	v_mfma_f32_32x32x16_bf16 v[34:49], v[182:185], v[190:193], v[34:49]
	v_mfma_f32_32x32x16_bf16 v[18:33], v[194:197], v[186:189], v[18:33]
	v_mfma_f32_32x32x16_bf16 v[2:17], v[194:197], v[190:193], v[2:17]
	ds_read_b128 v[182:185], v0 offset:36960
	ds_read_b128 v[186:189], v139 offset:55392
	ds_read_b128 v[190:193], v139 offset:60000
	ds_read_b128 v[194:197], v0 offset:41568
	s_waitcnt lgkmcnt(4)
	v_mfma_f32_32x32x16_bf16 v[50:65], v[166:169], v[170:173], v[50:65]
	v_mfma_f32_32x32x16_bf16 v[34:49], v[166:169], v[174:177], v[34:49]
	v_mfma_f32_32x32x16_bf16 v[18:33], v[178:181], v[170:173], v[18:33]
	v_mfma_f32_32x32x16_bf16 v[2:17], v[178:181], v[174:177], v[2:17]
	s_waitcnt lgkmcnt(0)
	v_mfma_f32_32x32x16_bf16 v[50:65], v[182:185], v[186:189], v[50:65]
	v_mfma_f32_32x32x16_bf16 v[34:49], v[182:185], v[190:193], v[34:49]
	v_mfma_f32_32x32x16_bf16 v[18:33], v[194:197], v[186:189], v[18:33]
	v_mfma_f32_32x32x16_bf16 v[2:17], v[194:197], v[190:193], v[2:17]
	s_setprio 0
	s_cmp_lt_u32 s3, 14
	s_waitcnt lgkmcnt(0)
	s_barrier
; #define TIDX (tid_launder())
; DI int crow(int reg, int hh) { return (reg & 3) + 8 * (reg >> 2) + 4 * hh; }
; template <int NJ>
; DI void acc_to_ct(const f32x16 (&acc)[2][NJ], float* Ct) {
;   const int lane = TIDX & 63, wid = TIDX >> 6, wm = wid >> 1, wn = wid & 1;
;   const int r = lane & 31, hh = lane >> 5;
; #pragma unroll
;   for (int i = 0; i < 2; ++i)
; #pragma unroll
;     for (int j = 0; j < NJ; ++j)
; #pragma unroll
;       for (int e = 0; e < 16; ++e) Ct[(wm * 64 + i * 32 + crow(e, hh)) * 132 + wn * 32 * NJ + j * 32 + r] = acc[i][j][e];
;   __syncthreads();
; DI void outproj_tile(const Params& p, int l, int mt, int tn, char* smem) {
;     ...
;     const int tid = TIDX, c = (tid & 31) * 4, row0 = tid >> 5;
;     float4 xa[16];
; #pragma unroll
;     for (int q = 0; q < 16; ++q) xa[q] = *(const float4*)(xo + (size_t)(m0 + row0 + 8 * q) * 1024 + tn * 128 + c);
	v_mov_b32_e32 v0, v230
	s_waitcnt vmcnt(1)
	v_mov_b32_e32 v66, v230
	v_and_b32_e32 v67, 31, v0
	v_lshrrev_b32_e32 v0, 3, v0
	v_and_b32_e32 v0, 4, v0
	v_lshrrev_b32_e32 v68, 1, v66
	v_and_or_b32 v0, v68, s47, v0
	v_and_or_b32 v66, v66, 64, v67
	v_mul_lo_u32 v0, v0, s79
	v_lshl_add_u32 v0, v66, 2, v0
	ds_write2_b32 v0, v50, v34 offset1:32
	ds_write2_b32 v0, v51, v35 offset0:132 offset1:164
	v_add_u32_e32 v34, 0x400, v0
	ds_write2_b32 v34, v52, v36 offset0:8 offset1:40
	ds_write2_b32 v34, v53, v37 offset0:140 offset1:172
	v_add_u32_e32 v34, 0x1000, v0
	ds_write2_b32 v34, v54, v38 offset0:32 offset1:64
	ds_write2_b32 v34, v55, v39 offset0:164 offset1:196
	v_add_u32_e32 v34, 0x1400, v0
	ds_write2_b32 v34, v56, v40 offset0:40 offset1:72
	ds_write2_b32 v34, v57, v41 offset0:172 offset1:204
	v_add_u32_e32 v34, 0x2000, v0
	ds_write2_b32 v34, v58, v42 offset0:64 offset1:96
	ds_write2_b32 v34, v59, v43 offset0:196 offset1:228
	v_add_u32_e32 v34, 0x2400, v0
	ds_write2_b32 v34, v60, v44 offset0:72 offset1:104
	ds_write2_b32 v34, v61, v45 offset0:204 offset1:236
	v_add_u32_e32 v34, 0x3000, v0
	ds_write2_b32 v34, v62, v46 offset0:96 offset1:128
	v_add_u32_e32 v34, 0x3200, v0
	ds_write2_b32 v34, v63, v47 offset0:100 offset1:132
	v_add_u32_e32 v34, 0x3400, v0
	ds_write2_b32 v34, v64, v48 offset0:104 offset1:136
	v_add_u32_e32 v34, 0x3600, v0
	ds_write2_b32 v34, v65, v49 offset0:108 offset1:140
	v_add_u32_e32 v34, 0x4000, v0
	ds_write2_b32 v34, v18, v2 offset0:128 offset1:160
	v_add_u32_e32 v2, 0x4400, v0
	ds_write2_b32 v2, v19, v3 offset0:4 offset1:36
	ds_write2_b32 v2, v20, v4 offset0:136 offset1:168
	v_add_u32_e32 v2, 0x4800, v0
	ds_write2_b32 v2, v21, v5 offset0:12 offset1:44
	v_add_u32_e32 v2, 0x5000, v0
	ds_write2_b32 v2, v22, v6 offset0:160 offset1:192
	v_add_u32_e32 v2, 0x5400, v0
	ds_write2_b32 v2, v23, v7 offset0:36 offset1:68
	ds_write2_b32 v2, v24, v8 offset0:168 offset1:200
	v_add_u32_e32 v2, 0x5800, v0
	ds_write2_b32 v2, v25, v9 offset0:44 offset1:76
	v_add_u32_e32 v2, 0x6000, v0
	ds_write2_b32 v2, v26, v10 offset0:192 offset1:224
	v_add_u32_e32 v2, 0x6400, v0
	ds_write2_b32 v2, v27, v11 offset0:68 offset1:100
	ds_write2_b32 v2, v28, v12 offset0:200 offset1:232
	v_add_u32_e32 v2, 0x6800, v0
	ds_write2_b32 v2, v29, v13 offset0:76 offset1:108
	v_add_u32_e32 v2, 0x7200, v0
	ds_write2_b32 v2, v30, v14 offset0:96 offset1:128
	v_add_u32_e32 v2, 0x7400, v0
	ds_write2_b32 v2, v31, v15 offset0:100 offset1:132
	v_add_u32_e32 v2, 0x7600, v0
	v_add_u32_e32 v0, 0x7800, v0
	ds_write2_b32 v0, v33, v17 offset0:108 offset1:140
	v_mov_b32_e32 v0, v230
	ds_write2_b32 v2, v32, v16 offset0:104 offset1:136
	s_waitcnt lgkmcnt(0)
	s_barrier
	s_lshl_b32 s14, s2, 2
	v_ashrrev_i32_e32 v68, 5, v0
	v_readlane_b32 s2, v254, 3
	v_add_u32_e32 v2, s1, v68
	v_readlane_b32 s3, v254, 4
	s_add_u32 s2, s2, s14
	v_lshlrev_b32_e32 v0, 4, v0
	s_addc_u32 s3, s3, 0
	v_and_b32_e32 v0, 0x1f0, v0
	v_ashrrev_i32_e32 v3, 31, v2
	v_lshl_add_u64 v[4:5], s[2:3], 0, v[0:1]
	v_lshlrev_b64 v[8:9], 12, v[2:3]
	s_mov_b64 s[2:3], 0x18000
	v_lshl_add_u64 v[20:21], v[8:9], 0, s[2:3]
	s_mov_b64 s[2:3], 0x20000
	v_lshl_add_u64 v[24:25], v[8:9], 0, s[2:3]
	s_mov_b64 s[2:3], 0x28000
	v_lshl_add_u64 v[28:29], v[8:9], 0, s[2:3]
	s_mov_b64 s[2:3], 0x30000
	v_lshl_add_u64 v[32:33], v[8:9], 0, s[2:3]
	s_mov_b64 s[2:3], 0x38000
	v_lshl_add_u64 v[36:37], v[8:9], 0, s[2:3]
	s_mov_b64 s[2:3], 0x40000
	v_lshl_add_u64 v[40:41], v[8:9], 0, s[2:3]
	s_mov_b64 s[2:3], 0x48000
	v_lshl_add_u64 v[44:45], v[8:9], 0, s[2:3]
	s_mov_b64 s[2:3], 0x50000
	v_lshl_add_u64 v[48:49], v[8:9], 0, s[2:3]
	s_mov_b64 s[2:3], 0x58000
	v_lshl_add_u64 v[52:53], v[8:9], 0, s[2:3]
	s_mov_b64 s[2:3], 0x60000
	v_lshl_add_u64 v[56:57], v[8:9], 0, s[2:3]
	s_mov_b64 s[2:3], 0x68000
	v_lshl_add_u64 v[60:61], v[8:9], 0, s[2:3]
	s_mov_b64 s[2:3], 0x70000
	v_lshl_add_u64 v[64:65], v[8:9], 0, s[2:3]
	s_mov_b64 s[2:3], 0x78000
	v_readlane_b32 s16, v252, 9
	v_lshl_add_u64 v[12:13], v[8:9], 0, s[48:49]
	v_lshl_add_u64 v[16:17], v[8:9], 0, s[40:41]
	v_lshl_add_u64 v[66:67], v[8:9], 0, s[2:3]
	v_readlane_b32 s22, v252, 15
	v_readlane_b32 s23, v252, 16
	v_lshl_add_u64 v[62:63], v[4:5], 0, v[8:9]
	v_lshl_add_u64 v[58:59], v[4:5], 0, v[12:13]
	v_lshl_add_u64 v[54:55], v[4:5], 0, v[16:17]
	v_lshl_add_u64 v[50:51], v[4:5], 0, v[20:21]
	v_lshl_add_u64 v[46:47], v[4:5], 0, v[24:25]
	v_lshl_add_u64 v[42:43], v[4:5], 0, v[28:29]
	v_lshl_add_u64 v[38:39], v[4:5], 0, v[32:33]
	v_lshl_add_u64 v[34:35], v[4:5], 0, v[36:37]
	v_lshl_add_u64 v[30:31], v[4:5], 0, v[40:41]
	v_lshl_add_u64 v[26:27], v[4:5], 0, v[44:45]
	v_lshl_add_u64 v[22:23], v[4:5], 0, v[48:49]
	v_lshl_add_u64 v[18:19], v[4:5], 0, v[52:53]
	v_lshl_add_u64 v[14:15], v[4:5], 0, v[56:57]
	v_lshl_add_u64 v[10:11], v[4:5], 0, v[60:61]
	v_lshl_add_u64 v[6:7], v[4:5], 0, v[64:65]
	v_lshl_add_u64 v[2:3], v[4:5], 0, v[66:67]
	v_lshl_add_u64 v[4:5], s[22:23], 0, v[8:9]
	v_lshl_add_u64 v[4:5], v[4:5], 0, s[14:15]
	v_lshl_add_u64 v[96:97], v[4:5], 0, v[0:1]
	v_lshl_add_u64 v[4:5], s[22:23], 0, v[12:13]
	v_lshl_add_u64 v[4:5], v[4:5], 0, s[14:15]
	v_lshl_add_u64 v[94:95], v[4:5], 0, v[0:1]
	v_lshl_add_u64 v[4:5], s[22:23], 0, v[16:17]
	v_lshl_add_u64 v[4:5], v[4:5], 0, s[14:15]
	v_lshl_add_u64 v[92:93], v[4:5], 0, v[0:1]
	v_lshl_add_u64 v[4:5], s[22:23], 0, v[20:21]
	v_lshl_add_u64 v[4:5], v[4:5], 0, s[14:15]
	v_lshl_add_u64 v[90:91], v[4:5], 0, v[0:1]
	v_lshl_add_u64 v[4:5], s[22:23], 0, v[24:25]
	v_lshl_add_u64 v[4:5], v[4:5], 0, s[14:15]
	v_lshl_add_u64 v[88:89], v[4:5], 0, v[0:1]
	v_lshl_add_u64 v[4:5], s[22:23], 0, v[28:29]
	v_lshl_add_u64 v[4:5], v[4:5], 0, s[14:15]
	v_lshl_add_u64 v[86:87], v[4:5], 0, v[0:1]
	v_lshl_add_u64 v[4:5], s[22:23], 0, v[32:33]
	v_lshl_add_u64 v[4:5], v[4:5], 0, s[14:15]
	v_lshl_add_u64 v[84:85], v[4:5], 0, v[0:1]
	v_lshl_add_u64 v[4:5], s[22:23], 0, v[36:37]
	v_lshl_add_u64 v[4:5], v[4:5], 0, s[14:15]
	v_lshl_add_u64 v[82:83], v[4:5], 0, v[0:1]
	v_lshl_add_u64 v[4:5], s[22:23], 0, v[40:41]
	v_lshl_add_u64 v[4:5], v[4:5], 0, s[14:15]
	v_lshl_add_u64 v[80:81], v[4:5], 0, v[0:1]
	v_lshl_add_u64 v[4:5], s[22:23], 0, v[44:45]
	v_lshl_add_u64 v[4:5], v[4:5], 0, s[14:15]
	v_lshl_add_u64 v[78:79], v[4:5], 0, v[0:1]
	v_lshl_add_u64 v[4:5], s[22:23], 0, v[48:49]
	v_lshl_add_u64 v[4:5], v[4:5], 0, s[14:15]
	v_lshl_add_u64 v[76:77], v[4:5], 0, v[0:1]
	v_lshl_add_u64 v[4:5], s[22:23], 0, v[52:53]
	v_lshl_add_u64 v[4:5], v[4:5], 0, s[14:15]
	v_lshl_add_u64 v[74:75], v[4:5], 0, v[0:1]
	v_lshl_add_u64 v[4:5], s[22:23], 0, v[56:57]
	v_lshl_add_u64 v[4:5], v[4:5], 0, s[14:15]
	s_waitcnt vmcnt(0)
; #define TIDX (tid_launder())
; DI void outproj_tile(const Params& p, int l, int mt, int tn, char* smem) {
;     ...
;     const int tid = TIDX, c = (tid & 31) * 4, row0 = tid >> 5;
;     float4 xa[16];
; #pragma unroll
;     for (int q = 0; q < 16; ++q) xa[q] = *(const float4*)(xo + (size_t)(m0 + row0 + 8 * q) * 1024 + tn * 128 + c);
; #pragma unroll
;     for (int q = 0; q < 16; ++q) {
;       const float4 cc = *(const float4*)(Ct + (row0 + 8 * q) * 132 + c);
;       *(float4*)(p.out + (size_t)(m0 + row0 + 8 * q) * 1024 + tn * 128 + c) = make_float4(xa[q].x + cc.x, xa[q].y + cc.y, xa[q].z + cc.z, xa[q].w + cc.w);
;     }
;   }
;   __syncthreads();
	v_lshl_add_u64 v[72:73], v[4:5], 0, v[0:1]
	v_lshl_add_u64 v[4:5], s[22:23], 0, v[60:61]
	v_lshl_add_u64 v[4:5], v[4:5], 0, s[14:15]
	v_lshl_add_u64 v[70:71], v[4:5], 0, v[0:1]
	v_lshl_add_u64 v[4:5], s[22:23], 0, v[64:65]
	v_lshl_add_u64 v[4:5], v[4:5], 0, s[14:15]
	v_mad_u64_u32 v[98:99], s[2:3], v68, s79, v[0:1]
	v_lshl_add_u64 v[68:69], v[4:5], 0, v[0:1]
	v_lshl_add_u64 v[4:5], s[22:23], 0, v[66:67]
	v_lshl_add_u64 v[4:5], v[4:5], 0, s[14:15]
	v_lshl_add_u64 v[66:67], v[4:5], 0, v[0:1]
	global_load_dwordx4 v[2:5], v[2:3], off
	ds_read_b128 v[166:169], v98 offset:63360
	ds_read_b128 v[170:173], v98 offset:59136
	ds_read_b128 v[174:177], v98 offset:54912
	ds_read_b128 v[178:181], v98 offset:50688
	ds_read_b128 v[182:185], v98 offset:46464
	ds_read_b128 v[186:189], v98 offset:42240
	ds_read_b128 v[190:193], v98 offset:38016
	ds_read_b128 v[194:197], v98 offset:33792
	ds_read_b128 v[198:201], v98 offset:29568
	global_load_dwordx4 v[6:9], v[6:7], off
	v_readlane_b32 s1, v250, 60
	global_load_dwordx4 v[10:13], v[10:11], off
	s_add_i32 s0, s0, s1
	global_load_dwordx4 v[14:17], v[14:15], off
	s_cmpk_gt_u32 s0, 0xff
	global_load_dwordx4 v[18:21], v[18:19], off
	v_readlane_b32 s17, v252, 10
	global_load_dwordx4 v[22:25], v[22:23], off
	v_readlane_b32 s18, v252, 11
	global_load_dwordx4 v[26:29], v[26:27], off
	v_readlane_b32 s19, v252, 12
	global_load_dwordx4 v[30:33], v[30:31], off
	v_readlane_b32 s20, v252, 13
	global_load_dwordx4 v[34:37], v[34:35], off
	v_readlane_b32 s21, v252, 14
	global_load_dwordx4 v[38:41], v[38:39], off
	v_readlane_b32 s24, v252, 17
	global_load_dwordx4 v[42:45], v[42:43], off
	v_readlane_b32 s25, v252, 18
	global_load_dwordx4 v[46:49], v[46:47], off
	v_readlane_b32 s26, v252, 19
	global_load_dwordx4 v[50:53], v[50:51], off
	v_readlane_b32 s27, v252, 20
	global_load_dwordx4 v[54:57], v[54:55], off
	v_readlane_b32 s28, v252, 21
	global_load_dwordx4 v[58:61], v[58:59], off
	v_readlane_b32 s29, v252, 22
	global_load_dwordx4 v[62:65], v[62:63], off
	v_readlane_b32 s30, v252, 23
	v_readlane_b32 s31, v252, 24
	s_waitcnt vmcnt(15)
	s_waitcnt lgkmcnt(8)
	v_pk_add_f32 v[2:3], v[2:3], v[166:167]
	v_pk_add_f32 v[4:5], v[4:5], v[168:169]
	ds_read_b128 v[166:169], v98 offset:25344
	s_waitcnt vmcnt(14)
	s_waitcnt lgkmcnt(8)
	v_pk_add_f32 v[6:7], v[6:7], v[170:171]
	v_pk_add_f32 v[8:9], v[8:9], v[172:173]
	ds_read_b128 v[170:173], v98 offset:21120
	s_waitcnt vmcnt(13)
	s_waitcnt lgkmcnt(8)
	v_pk_add_f32 v[10:11], v[10:11], v[174:175]
	v_pk_add_f32 v[12:13], v[12:13], v[176:177]
	ds_read_b128 v[174:177], v98 offset:16896
	s_waitcnt vmcnt(12)
	s_waitcnt lgkmcnt(8)
	v_pk_add_f32 v[14:15], v[14:15], v[178:179]
	v_pk_add_f32 v[16:17], v[16:17], v[180:181]
	ds_read_b128 v[178:181], v98 offset:12672
	s_waitcnt vmcnt(11)
	s_waitcnt lgkmcnt(8)
	v_pk_add_f32 v[18:19], v[18:19], v[182:183]
	v_pk_add_f32 v[20:21], v[20:21], v[184:185]
	ds_read_b128 v[182:185], v98 offset:8448
	s_waitcnt vmcnt(10)
	s_waitcnt lgkmcnt(8)
	v_pk_add_f32 v[22:23], v[22:23], v[186:187]
	v_pk_add_f32 v[24:25], v[24:25], v[188:189]
	ds_read_b128 v[186:189], v98 offset:4224
	s_waitcnt vmcnt(9)
	s_waitcnt lgkmcnt(8)
	v_pk_add_f32 v[26:27], v[26:27], v[190:191]
	v_pk_add_f32 v[28:29], v[28:29], v[192:193]
	ds_read_b128 v[190:193], v98
	s_waitcnt vmcnt(8)
	s_waitcnt lgkmcnt(8)
	v_pk_add_f32 v[30:31], v[30:31], v[194:195]
	v_pk_add_f32 v[32:33], v[32:33], v[196:197]
	s_waitcnt vmcnt(7)
	s_waitcnt lgkmcnt(7)
	v_pk_add_f32 v[34:35], v[34:35], v[198:199]
	v_pk_add_f32 v[36:37], v[36:37], v[200:201]
	s_waitcnt vmcnt(6)
	s_waitcnt lgkmcnt(6)
	v_pk_add_f32 v[38:39], v[38:39], v[166:167]
	v_pk_add_f32 v[40:41], v[40:41], v[168:169]
	s_waitcnt vmcnt(5)
	s_waitcnt lgkmcnt(5)
	v_pk_add_f32 v[42:43], v[42:43], v[170:171]
	v_pk_add_f32 v[44:45], v[44:45], v[172:173]
	s_waitcnt vmcnt(4)
	s_waitcnt lgkmcnt(4)
	v_pk_add_f32 v[46:47], v[46:47], v[174:175]
	v_pk_add_f32 v[48:49], v[48:49], v[176:177]
	s_waitcnt vmcnt(3)
	s_waitcnt lgkmcnt(3)
	v_pk_add_f32 v[50:51], v[50:51], v[178:179]
	v_pk_add_f32 v[52:53], v[52:53], v[180:181]
	s_waitcnt vmcnt(2)
	s_waitcnt lgkmcnt(2)
	v_pk_add_f32 v[54:55], v[54:55], v[182:183]
	v_pk_add_f32 v[56:57], v[56:57], v[184:185]
	s_waitcnt vmcnt(1)
	s_waitcnt lgkmcnt(1)
	v_pk_add_f32 v[58:59], v[58:59], v[186:187]
	v_pk_add_f32 v[60:61], v[60:61], v[188:189]
	s_waitcnt vmcnt(0)
	s_waitcnt lgkmcnt(0)
	v_pk_add_f32 v[62:63], v[62:63], v[190:191]
	v_pk_add_f32 v[64:65], v[64:65], v[192:193]
	global_store_dwordx4 v[96:97], v[62:65], off
	global_store_dwordx4 v[94:95], v[58:61], off
	global_store_dwordx4 v[92:93], v[54:57], off
	global_store_dwordx4 v[90:91], v[50:53], off
	global_store_dwordx4 v[88:89], v[46:49], off
	global_store_dwordx4 v[86:87], v[42:45], off
	global_store_dwordx4 v[84:85], v[38:41], off
	global_store_dwordx4 v[82:83], v[34:37], off
	global_store_dwordx4 v[80:81], v[30:33], off
	global_store_dwordx4 v[78:79], v[26:29], off
	global_store_dwordx4 v[76:77], v[22:25], off
	global_store_dwordx4 v[74:75], v[18:21], off
	global_store_dwordx4 v[72:73], v[14:17], off
	global_store_dwordx4 v[70:71], v[10:13], off
	global_store_dwordx4 v[68:69], v[6:9], off
	global_store_dwordx4 v[66:67], v[2:5], off
	s_barrier
	s_cbranch_scc0 .LBB0_11

; #define TIDX (tid_launder())
; DI unsigned pack2(float a, float b) { hwf2 v = {a, b}; hwbf2 r = __builtin_convertvector(v, hwbf2); return __builtin_bit_cast(unsigned, r); }
; DI float siluf(float x) { return x * __builtin_amdgcn_rcpf(1.f + __expf(-x)); }
; DI void epi_store64(const float* Ct, int cb, const float* rn, int grp, const float* gain, bool silu, const float* bias,
;                     bf16_t* dst, size_t ldd, int dcol0, int m0, int Mmax) {
;   const int tid = TIDX, c = (tid & 15) * 4;
;   float4 gv = make_float4(1.f, 1.f, 1.f, 1.f), bv = make_float4(0.f, 0.f, 0.f, 0.f);
;   if (rn) gv = *(const float4*)(gain + c);
;   if (bias) bv = *(const float4*)(bias + c);
; #pragma unroll
;   for (int q = 0; q < 8; ++q) {
;     const int row = (tid >> 4) + 16 * q;
;     float4 v = *(const float4*)(Ct + row * 132 + cb + c);
;     v.x += bv.x; v.y += bv.y; v.z += bv.z; v.w += bv.w;
;     if (rn) { const float sc = rn[row * 2 + grp]; v.x *= sc * gv.x; v.y *= sc * gv.y; v.z *= sc * gv.z; v.w *= sc * gv.w; }
;     if (silu) { v.x = siluf(v.x); v.y = siluf(v.y); v.z = siluf(v.z); v.w = siluf(v.w); }
;     uint2 o; o.x = pack2(v.x, v.y); o.y = pack2(v.z, v.w);
;     *(uint2*)(dst + (size_t)(m0 + row) * ldd + dcol0 + c) = o;
;   }
; }
; DI void inproj_tile(const Params& p, int l, int mt, int tn, char* smem) {
;     ...
;   } else if (tn <= 24) {
;     const int c0 = (tn - 13) * 128;
;     epi_store64(Ct, 0, nullptr, 0, nullptr, false, nullptr, p.projB, LDA_B, c0, m0, T_TOK);
;     epi_store64(Ct, 64, nullptr, 0, nullptr, false, nullptr, p.projB, LDA_B, c0 + 64, m0, T_TOK);
.LBB0_1965:
	s_andn2_b64 vcc, exec, s[0:1]
	s_cbranch_vccnz .LBB0_1967
	v_mov_b32_e32 v0, v230
	v_readlane_b32 s16, v252, 57
	s_lshl_b64 s[0:1], s[2:3], 1
	v_lshlrev_b32_e32 v2, 2, v0
	v_readlane_b32 s26, v253, 3
	v_and_b32_e32 v4, 60, v2
	v_readlane_b32 s27, v253, 4
	s_add_u32 s0, s26, s0
	v_ashrrev_i32_e32 v8, 4, v0
	s_addc_u32 s1, s27, s1
	v_lshlrev_b32_e32 v0, 1, v4
	v_lshl_add_u64 v[2:3], s[0:1], 0, v[0:1]
	v_mul_lo_u32 v0, v8, s79
	v_lshl_add_u32 v0, v4, 2, v0
	ds_read_b128 v[72:75], v0
	ds_read_b128 v[76:79], v0 offset:8448
	ds_read_b128 v[80:83], v0 offset:16896
	ds_read_b128 v[84:87], v0 offset:25344
	ds_read_b128 v[88:91], v0 offset:33792
	ds_read_b128 v[92:95], v0 offset:42240
	ds_read_b128 v[96:99], v0 offset:50688
	ds_read_b128 v[100:103], v0 offset:59136
	v_add_u32_e32 v8, s11, v8
	s_movk_i32 s3, 0xc00
	v_readlane_b32 s17, v252, 58
	v_readlane_b32 s18, v252, 59
	s_waitcnt lgkmcnt(7)
	v_pk_add_f32 v[4:5], v[72:73], 0 op_sel_hi:[1, 0]
	v_pk_add_f32 v[6:7], v[74:75], 0 op_sel_hi:[1, 0]
	v_cvt_pk_bf16_f32 v4, v4, v5
	v_cvt_pk_bf16_f32 v5, v6, v7
	v_mad_i64_i32 v[6:7], s[6:7], v8, s3, v[2:3]
	global_store_dwordx2 v[6:7], v[4:5], off offset:-3328
	v_readlane_b32 s19, v252, 60
	v_readlane_b32 s20, v252, 61
	v_readlane_b32 s21, v252, 62
	v_readlane_b32 s22, v252, 63
	s_waitcnt lgkmcnt(6)
	v_pk_add_f32 v[4:5], v[76:77], 0 op_sel_hi:[1, 0]
	v_pk_add_f32 v[6:7], v[78:79], 0 op_sel_hi:[1, 0]
	v_cvt_pk_bf16_f32 v4, v4, v5
	v_cvt_pk_bf16_f32 v5, v6, v7
	v_add_u32_e32 v6, 16, v8
	v_mad_i64_i32 v[6:7], s[6:7], v6, s3, v[2:3]
	global_store_dwordx2 v[6:7], v[4:5], off offset:-3328
	v_readlane_b32 s23, v253, 0
	v_readlane_b32 s24, v253, 1
	v_readlane_b32 s25, v253, 2
	v_readlane_b32 s28, v253, 5
	s_waitcnt lgkmcnt(5)
	v_pk_add_f32 v[4:5], v[80:81], 0 op_sel_hi:[1, 0]
	v_pk_add_f32 v[6:7], v[82:83], 0 op_sel_hi:[1, 0]
	v_cvt_pk_bf16_f32 v4, v4, v5
	v_cvt_pk_bf16_f32 v5, v6, v7
	v_add_u32_e32 v6, 32, v8
	v_mad_i64_i32 v[6:7], s[6:7], v6, s3, v[2:3]
	global_store_dwordx2 v[6:7], v[4:5], off offset:-3328
	v_readlane_b32 s29, v253, 6
	v_readlane_b32 s30, v253, 7
	v_readlane_b32 s31, v253, 8
	s_waitcnt lgkmcnt(4)
	v_pk_add_f32 v[4:5], v[84:85], 0 op_sel_hi:[1, 0]
	v_pk_add_f32 v[6:7], v[86:87], 0 op_sel_hi:[1, 0]
	v_cvt_pk_bf16_f32 v4, v4, v5
	v_cvt_pk_bf16_f32 v5, v6, v7
	v_add_u32_e32 v6, 48, v8
	v_mad_i64_i32 v[6:7], s[6:7], v6, s3, v[2:3]
	global_store_dwordx2 v[6:7], v[4:5], off offset:-3328
	s_waitcnt lgkmcnt(3)
	v_pk_add_f32 v[4:5], v[88:89], 0 op_sel_hi:[1, 0]
	v_pk_add_f32 v[6:7], v[90:91], 0 op_sel_hi:[1, 0]
	v_cvt_pk_bf16_f32 v4, v4, v5
	v_cvt_pk_bf16_f32 v5, v6, v7
	v_add_u32_e32 v6, 64, v8
	v_mad_i64_i32 v[6:7], s[6:7], v6, s3, v[2:3]
	global_store_dwordx2 v[6:7], v[4:5], off offset:-3328
	s_waitcnt lgkmcnt(2)
	v_pk_add_f32 v[4:5], v[92:93], 0 op_sel_hi:[1, 0]
	v_pk_add_f32 v[6:7], v[94:95], 0 op_sel_hi:[1, 0]
	v_cvt_pk_bf16_f32 v4, v4, v5
	v_cvt_pk_bf16_f32 v5, v6, v7
	v_add_u32_e32 v6, 0x50, v8
	v_mad_i64_i32 v[6:7], s[6:7], v6, s3, v[2:3]
	global_store_dwordx2 v[6:7], v[4:5], off offset:-3328
	s_waitcnt lgkmcnt(1)
	v_pk_add_f32 v[4:5], v[96:97], 0 op_sel_hi:[1, 0]
	v_pk_add_f32 v[6:7], v[98:99], 0 op_sel_hi:[1, 0]
	v_cvt_pk_bf16_f32 v4, v4, v5
	v_cvt_pk_bf16_f32 v5, v6, v7
	v_add_u32_e32 v6, 0x60, v8
	v_mad_i64_i32 v[6:7], s[6:7], v6, s3, v[2:3]
	global_store_dwordx2 v[6:7], v[4:5], off offset:-3328
	v_add_u32_e32 v0, 0x70, v8
	v_mad_i64_i32 v[2:3], s[6:7], v0, s3, v[2:3]
	v_mov_b32_e32 v0, v230
	s_waitcnt lgkmcnt(0)
	v_pk_add_f32 v[4:5], v[100:101], 0 op_sel_hi:[1, 0]
	v_pk_add_f32 v[6:7], v[102:103], 0 op_sel_hi:[1, 0]
	v_cvt_pk_bf16_f32 v4, v4, v5
	v_cvt_pk_bf16_f32 v5, v6, v7
	global_store_dwordx2 v[2:3], v[4:5], off offset:-3328
	s_nop 0
	v_lshlrev_b32_e32 v2, 2, v0
	v_and_b32_e32 v4, 60, v2
	v_ashrrev_i32_e32 v8, 4, v0
	v_lshlrev_b32_e32 v0, 1, v4
	v_lshl_add_u64 v[2:3], s[0:1], 0, v[0:1]
	v_mul_lo_u32 v0, v8, s79
	v_lshl_add_u32 v0, v4, 2, v0
	ds_read_b128 v[72:75], v0 offset:256
	ds_read_b128 v[76:79], v0 offset:8704
	ds_read_b128 v[80:83], v0 offset:17152
	ds_read_b128 v[84:87], v0 offset:25600
	ds_read_b128 v[88:91], v0 offset:34048
	ds_read_b128 v[92:95], v0 offset:42496
	ds_read_b128 v[96:99], v0 offset:50944
	ds_read_b128 v[100:103], v0 offset:59392
	v_add_u32_e32 v8, s11, v8
	s_waitcnt lgkmcnt(7)
	v_pk_add_f32 v[4:5], v[72:73], 0 op_sel_hi:[1, 0]
	v_pk_add_f32 v[6:7], v[74:75], 0 op_sel_hi:[1, 0]
	v_cvt_pk_bf16_f32 v4, v4, v5
	v_cvt_pk_bf16_f32 v5, v6, v7
	v_mad_i64_i32 v[6:7], s[0:1], v8, s3, v[2:3]
	global_store_dwordx2 v[6:7], v[4:5], off offset:-3200
	s_waitcnt lgkmcnt(6)
	v_pk_add_f32 v[4:5], v[76:77], 0 op_sel_hi:[1, 0]
	v_pk_add_f32 v[6:7], v[78:79], 0 op_sel_hi:[1, 0]
	v_cvt_pk_bf16_f32 v4, v4, v5
	v_cvt_pk_bf16_f32 v5, v6, v7
	v_add_u32_e32 v6, 16, v8
	v_mad_i64_i32 v[6:7], s[0:1], v6, s3, v[2:3]
	global_store_dwordx2 v[6:7], v[4:5], off offset:-3200
	s_waitcnt lgkmcnt(5)
	v_pk_add_f32 v[4:5], v[80:81], 0 op_sel_hi:[1, 0]
	v_pk_add_f32 v[6:7], v[82:83], 0 op_sel_hi:[1, 0]
	v_cvt_pk_bf16_f32 v4, v4, v5
	v_cvt_pk_bf16_f32 v5, v6, v7
	v_add_u32_e32 v6, 32, v8
	v_mad_i64_i32 v[6:7], s[0:1], v6, s3, v[2:3]
	global_store_dwordx2 v[6:7], v[4:5], off offset:-3200
	s_waitcnt lgkmcnt(4)
	v_pk_add_f32 v[4:5], v[84:85], 0 op_sel_hi:[1, 0]
	v_pk_add_f32 v[6:7], v[86:87], 0 op_sel_hi:[1, 0]
	v_cvt_pk_bf16_f32 v4, v4, v5
	v_cvt_pk_bf16_f32 v5, v6, v7
	v_add_u32_e32 v6, 48, v8
	v_mad_i64_i32 v[6:7], s[0:1], v6, s3, v[2:3]
	global_store_dwordx2 v[6:7], v[4:5], off offset:-3200
	s_waitcnt lgkmcnt(3)
	v_pk_add_f32 v[4:5], v[88:89], 0 op_sel_hi:[1, 0]
	v_pk_add_f32 v[6:7], v[90:91], 0 op_sel_hi:[1, 0]
	v_cvt_pk_bf16_f32 v4, v4, v5
	v_cvt_pk_bf16_f32 v5, v6, v7
	v_add_u32_e32 v6, 64, v8
	v_mad_i64_i32 v[6:7], s[0:1], v6, s3, v[2:3]
	global_store_dwordx2 v[6:7], v[4:5], off offset:-3200
	s_waitcnt lgkmcnt(2)
	v_pk_add_f32 v[4:5], v[92:93], 0 op_sel_hi:[1, 0]
	v_pk_add_f32 v[6:7], v[94:95], 0 op_sel_hi:[1, 0]
	v_cvt_pk_bf16_f32 v4, v4, v5
	v_cvt_pk_bf16_f32 v5, v6, v7
	v_add_u32_e32 v6, 0x50, v8
	v_mad_i64_i32 v[6:7], s[0:1], v6, s3, v[2:3]
	global_store_dwordx2 v[6:7], v[4:5], off offset:-3200
	s_waitcnt lgkmcnt(1)
	v_pk_add_f32 v[4:5], v[96:97], 0 op_sel_hi:[1, 0]
	v_pk_add_f32 v[6:7], v[98:99], 0 op_sel_hi:[1, 0]
	v_cvt_pk_bf16_f32 v4, v4, v5
	v_cvt_pk_bf16_f32 v5, v6, v7
	v_add_u32_e32 v6, 0x60, v8
	v_mad_i64_i32 v[6:7], s[0:1], v6, s3, v[2:3]
	global_store_dwordx2 v[6:7], v[4:5], off offset:-3200
	v_add_u32_e32 v0, 0x70, v8
	v_mad_i64_i32 v[2:3], s[0:1], v0, s3, v[2:3]
	s_waitcnt lgkmcnt(0)
	v_pk_add_f32 v[4:5], v[100:101], 0 op_sel_hi:[1, 0]
	v_pk_add_f32 v[6:7], v[102:103], 0 op_sel_hi:[1, 0]
	v_cvt_pk_bf16_f32 v4, v4, v5
	v_cvt_pk_bf16_f32 v5, v6, v7
	global_store_dwordx2 v[2:3], v[4:5], off offset:-3200

; #define TIDX (tid_launder())
; DI void epi_rownorm(const float* Ct, float* rn, int W) {
;   const int row = TIDX >> 1, grp = TIDX & 1;
;   float ss = 0.f;
;   for (int c0 = 0; c0 < 64; ++c0) { const int c = (c0 + row) & 63; const float v = Ct[row * 132 + grp * 64 + c]; ss += v * v; }
;   if (W == 128) { ss += __shfl_xor(ss, 1); ss *= 0.5f; }
;   rn[row * 2 + grp] = rsqrtf(ss * (1.f / 64.f) + 1e-6f);
.LBB0_2012:
	s_andn2_b64 vcc, exec, s[0:1]
	s_cbranch_vccnz .LBB0_2041
	s_cmp_gt_i32 s12, 9
	s_mov_b64 s[0:1], -1
	s_cbranch_scc0 .LBB0_2039
	v_mov_b32_e32 v0, v230
	v_mov_b32_e32 v2, v230
	s_mov_b32 s0, 0x800000
	v_ashrrev_i32_e32 v3, 1, v0
	v_and_b32_e32 v2, 1, v2
	v_mul_lo_u32 v4, v3, s79
	v_add_u32_e32 v7, 55, v3
	v_lshl_add_u32 v4, v2, 8, v4
	v_and_b32_e32 v5, 63, v3
	v_and_b32_e32 v7, 63, v7
	v_lshl_add_u32 v5, v5, 2, v4
	v_lshl_add_u32 v7, v7, 2, v4
	ds_read_b32 v6, v5
	ds_read_b32 v7, v7
	v_add_u32_e32 v5, 1, v3
	v_and_b32_e32 v5, 63, v5
	v_lshl_add_u32 v5, v5, 2, v4
	ds_read_b32 v5, v5
	v_readlane_b32 s16, v252, 57
	v_readlane_b32 s24, v253, 1
	v_readlane_b32 s25, v253, 2
	v_mov_b32_e32 v18, v230
	s_waitcnt lgkmcnt(0)
	v_mul_f32_e32 v5, v5, v5
	v_fmac_f32_e32 v5, v6, v6
	v_add_u32_e32 v6, 2, v3
	v_and_b32_e32 v6, 63, v6
	v_lshl_add_u32 v6, v6, 2, v4
	ds_read_b32 v6, v6
	s_mov_b64 s[6:7], -1
	s_waitcnt vmcnt(4)
	v_mov_b32_e32 v11, 1.0
	v_mov_b32_e32 v10, 1.0
	v_readlane_b32 s17, v252, 58
	s_waitcnt lgkmcnt(0)
	v_fmac_f32_e32 v5, v6, v6
	v_add_u32_e32 v6, 3, v3
	v_and_b32_e32 v6, 63, v6
	v_lshl_add_u32 v6, v6, 2, v4
	ds_read_b32 v6, v6
	v_readlane_b32 s18, v252, 59
	v_readlane_b32 s19, v252, 60
	v_readlane_b32 s20, v252, 61
	v_readlane_b32 s21, v252, 62
	s_waitcnt lgkmcnt(0)
	v_fmac_f32_e32 v5, v6, v6
	v_add_u32_e32 v6, 4, v3
	v_and_b32_e32 v6, 63, v6
	v_lshl_add_u32 v6, v6, 2, v4
	ds_read_b32 v6, v6
	v_readlane_b32 s22, v252, 63
	v_readlane_b32 s23, v253, 0
	v_readlane_b32 s26, v253, 3
	v_readlane_b32 s27, v253, 4
	s_waitcnt lgkmcnt(0)
	v_fmac_f32_e32 v5, v6, v6
	v_add_u32_e32 v6, 5, v3
	v_and_b32_e32 v6, 63, v6
	v_lshl_add_u32 v6, v6, 2, v4
	ds_read_b32 v6, v6
	v_readlane_b32 s28, v253, 5
	v_readlane_b32 s29, v253, 6
	v_readlane_b32 s30, v253, 7
	v_readlane_b32 s31, v253, 8
	s_waitcnt lgkmcnt(0)
	v_fmac_f32_e32 v5, v6, v6
	v_add_u32_e32 v6, 6, v3
	v_and_b32_e32 v6, 63, v6
	v_lshl_add_u32 v6, v6, 2, v4
	ds_read_b32 v6, v6
	s_waitcnt lgkmcnt(0)
	v_fmac_f32_e32 v5, v6, v6
	v_add_u32_e32 v6, 7, v3
	v_and_b32_e32 v6, 63, v6
	v_lshl_add_u32 v6, v6, 2, v4
	ds_read_b32 v6, v6
	s_waitcnt lgkmcnt(0)
	v_fmac_f32_e32 v5, v6, v6
	v_add_u32_e32 v6, 8, v3
	v_and_b32_e32 v6, 63, v6
	v_lshl_add_u32 v6, v6, 2, v4
	ds_read_b32 v6, v6
	s_waitcnt lgkmcnt(0)
	v_fmac_f32_e32 v5, v6, v6
	v_add_u32_e32 v6, 9, v3
	v_and_b32_e32 v6, 63, v6
	v_lshl_add_u32 v6, v6, 2, v4
	ds_read_b32 v6, v6
	s_waitcnt lgkmcnt(0)
	v_fmac_f32_e32 v5, v6, v6
	v_add_u32_e32 v6, 10, v3
	v_and_b32_e32 v6, 63, v6
	v_lshl_add_u32 v6, v6, 2, v4
	ds_read_b32 v6, v6
	s_waitcnt lgkmcnt(0)
	v_fmac_f32_e32 v5, v6, v6
	v_add_u32_e32 v6, 11, v3
	v_and_b32_e32 v6, 63, v6
	v_lshl_add_u32 v6, v6, 2, v4
	ds_read_b32 v6, v6
	s_waitcnt lgkmcnt(0)
	v_fmac_f32_e32 v5, v6, v6
	v_add_u32_e32 v6, 12, v3
	v_and_b32_e32 v6, 63, v6
	v_lshl_add_u32 v6, v6, 2, v4
	ds_read_b32 v6, v6
	s_waitcnt lgkmcnt(0)
	v_fmac_f32_e32 v5, v6, v6
	v_add_u32_e32 v6, 13, v3
	v_and_b32_e32 v6, 63, v6
	v_lshl_add_u32 v6, v6, 2, v4
	ds_read_b32 v6, v6
	s_waitcnt lgkmcnt(0)
	v_fmac_f32_e32 v5, v6, v6
	v_add_u32_e32 v6, 14, v3
	v_and_b32_e32 v6, 63, v6
	v_lshl_add_u32 v6, v6, 2, v4
	ds_read_b32 v6, v6
	s_waitcnt lgkmcnt(0)
	v_fmac_f32_e32 v5, v6, v6
	v_add_u32_e32 v6, 15, v3
	v_and_b32_e32 v6, 63, v6
	v_lshl_add_u32 v6, v6, 2, v4
	ds_read_b32 v6, v6
	s_waitcnt lgkmcnt(0)
	v_fmac_f32_e32 v5, v6, v6
	v_add_u32_e32 v6, 16, v3
	v_and_b32_e32 v6, 63, v6
	v_lshl_add_u32 v6, v6, 2, v4
	ds_read_b32 v6, v6
	s_waitcnt lgkmcnt(0)
	v_fmac_f32_e32 v5, v6, v6
	v_add_u32_e32 v6, 17, v3
	v_and_b32_e32 v6, 63, v6
	v_lshl_add_u32 v6, v6, 2, v4
	ds_read_b32 v6, v6
	s_waitcnt lgkmcnt(0)
	v_fmac_f32_e32 v5, v6, v6
	v_add_u32_e32 v6, 18, v3
	v_and_b32_e32 v6, 63, v6
	v_lshl_add_u32 v6, v6, 2, v4
	ds_read_b32 v6, v6
	s_waitcnt lgkmcnt(0)
	v_fmac_f32_e32 v5, v6, v6
	v_add_u32_e32 v6, 19, v3
	v_and_b32_e32 v6, 63, v6
	v_lshl_add_u32 v6, v6, 2, v4
	ds_read_b32 v6, v6
	s_waitcnt lgkmcnt(0)
	v_fmac_f32_e32 v5, v6, v6
	v_add_u32_e32 v6, 20, v3
	v_and_b32_e32 v6, 63, v6
	v_lshl_add_u32 v6, v6, 2, v4
	ds_read_b32 v6, v6
	s_waitcnt lgkmcnt(0)
	v_fmac_f32_e32 v5, v6, v6
	v_add_u32_e32 v6, 21, v3
	v_and_b32_e32 v6, 63, v6
	v_lshl_add_u32 v6, v6, 2, v4
	ds_read_b32 v6, v6
	s_waitcnt lgkmcnt(0)
	v_fmac_f32_e32 v5, v6, v6
	v_add_u32_e32 v6, 22, v3
	v_and_b32_e32 v6, 63, v6
	v_lshl_add_u32 v6, v6, 2, v4
	ds_read_b32 v6, v6
	s_waitcnt lgkmcnt(0)
	v_fmac_f32_e32 v5, v6, v6
	v_add_u32_e32 v6, 23, v3
	v_and_b32_e32 v6, 63, v6
	v_lshl_add_u32 v6, v6, 2, v4
	ds_read_b32 v6, v6
	s_waitcnt lgkmcnt(0)
	v_fmac_f32_e32 v5, v6, v6
	v_add_u32_e32 v6, 24, v3
	v_and_b32_e32 v6, 63, v6
	v_lshl_add_u32 v6, v6, 2, v4
	ds_read_b32 v6, v6
	s_waitcnt lgkmcnt(0)
	v_fmac_f32_e32 v5, v6, v6
	v_add_u32_e32 v6, 25, v3
	v_and_b32_e32 v6, 63, v6
	v_lshl_add_u32 v6, v6, 2, v4
	ds_read_b32 v6, v6
	s_waitcnt lgkmcnt(0)
	v_fmac_f32_e32 v5, v6, v6
	v_add_u32_e32 v6, 26, v3
	v_and_b32_e32 v6, 63, v6
	v_lshl_add_u32 v6, v6, 2, v4
	ds_read_b32 v6, v6
	s_waitcnt lgkmcnt(0)
	v_fmac_f32_e32 v5, v6, v6
	v_add_u32_e32 v6, 27, v3
	v_and_b32_e32 v6, 63, v6
	v_lshl_add_u32 v6, v6, 2, v4
	ds_read_b32 v6, v6
	s_waitcnt lgkmcnt(0)
	v_fmac_f32_e32 v5, v6, v6
	v_add_u32_e32 v6, 28, v3
	v_and_b32_e32 v6, 63, v6
	v_lshl_add_u32 v6, v6, 2, v4
	ds_read_b32 v6, v6
	s_waitcnt lgkmcnt(0)
	v_fmac_f32_e32 v5, v6, v6
	v_add_u32_e32 v6, 29, v3
	v_and_b32_e32 v6, 63, v6
	v_lshl_add_u32 v6, v6, 2, v4
	ds_read_b32 v6, v6
	s_waitcnt lgkmcnt(0)
	v_fmac_f32_e32 v5, v6, v6
	v_add_u32_e32 v6, 30, v3
	v_and_b32_e32 v6, 63, v6
	v_lshl_add_u32 v6, v6, 2, v4
	ds_read_b32 v6, v6
	s_waitcnt lgkmcnt(0)
; DI void epi_rownorm(const float* Ct, float* rn, int W) {
;     ...
;   for (int c0 = 0; c0 < 64; ++c0) { const int c = (c0 + row) & 63; const float v = Ct[row * 132 + grp * 64 + c]; ss += v * v; }
;   if (W == 128) { ss += __shfl_xor(ss, 1); ss *= 0.5f; }
;   rn[row * 2 + grp] = rsqrtf(ss * (1.f / 64.f) + 1e-6f);
;   __syncthreads();
	v_fmac_f32_e32 v5, v6, v6
	v_add_u32_e32 v6, 31, v3
	v_and_b32_e32 v6, 63, v6
	v_lshl_add_u32 v6, v6, 2, v4
	ds_read_b32 v6, v6
	s_waitcnt lgkmcnt(0)
	v_fmac_f32_e32 v5, v6, v6
	v_bitop3_b32 v6, v3, 32, 63 bitop3:0x6c
	v_lshl_add_u32 v6, v6, 2, v4
	ds_read_b32 v6, v6
	s_waitcnt lgkmcnt(0)
	v_fmac_f32_e32 v5, v6, v6
	v_add_u32_e32 v6, 33, v3
	v_and_b32_e32 v6, 63, v6
	v_lshl_add_u32 v6, v6, 2, v4
	ds_read_b32 v6, v6
	s_waitcnt lgkmcnt(0)
	v_fmac_f32_e32 v5, v6, v6
	v_add_u32_e32 v6, 34, v3
	v_and_b32_e32 v6, 63, v6
	v_lshl_add_u32 v6, v6, 2, v4
	ds_read_b32 v6, v6
	s_waitcnt lgkmcnt(0)
	v_fmac_f32_e32 v5, v6, v6
	v_add_u32_e32 v6, 35, v3
	v_and_b32_e32 v6, 63, v6
	v_lshl_add_u32 v6, v6, 2, v4
	ds_read_b32 v6, v6
	s_waitcnt lgkmcnt(0)
	v_fmac_f32_e32 v5, v6, v6
	v_add_u32_e32 v6, 36, v3
	v_and_b32_e32 v6, 63, v6
	v_lshl_add_u32 v6, v6, 2, v4
	ds_read_b32 v6, v6
	s_waitcnt lgkmcnt(0)
	v_fmac_f32_e32 v5, v6, v6
	v_add_u32_e32 v6, 37, v3
	v_and_b32_e32 v6, 63, v6
	v_lshl_add_u32 v6, v6, 2, v4
	ds_read_b32 v6, v6
	s_waitcnt lgkmcnt(0)
	v_fmac_f32_e32 v5, v6, v6
	v_add_u32_e32 v6, 38, v3
	v_and_b32_e32 v6, 63, v6
	v_lshl_add_u32 v6, v6, 2, v4
	ds_read_b32 v6, v6
	s_waitcnt lgkmcnt(0)
	v_fmac_f32_e32 v5, v6, v6
	v_add_u32_e32 v6, 39, v3
	v_and_b32_e32 v6, 63, v6
	v_lshl_add_u32 v6, v6, 2, v4
	ds_read_b32 v6, v6
	s_waitcnt lgkmcnt(0)
	v_fmac_f32_e32 v5, v6, v6
	v_add_u32_e32 v6, 40, v3
	v_and_b32_e32 v6, 63, v6
	v_lshl_add_u32 v6, v6, 2, v4
	ds_read_b32 v6, v6
	s_waitcnt lgkmcnt(0)
	v_fmac_f32_e32 v5, v6, v6
	v_add_u32_e32 v6, 41, v3
	v_and_b32_e32 v6, 63, v6
	v_lshl_add_u32 v6, v6, 2, v4
	ds_read_b32 v6, v6
	s_waitcnt lgkmcnt(0)
	v_fmac_f32_e32 v5, v6, v6
	v_add_u32_e32 v6, 42, v3
	v_and_b32_e32 v6, 63, v6
	v_lshl_add_u32 v6, v6, 2, v4
	ds_read_b32 v6, v6
	s_waitcnt lgkmcnt(0)
	v_fmac_f32_e32 v5, v6, v6
	v_add_u32_e32 v6, 43, v3
	v_and_b32_e32 v6, 63, v6
	v_lshl_add_u32 v6, v6, 2, v4
	ds_read_b32 v6, v6
	s_waitcnt lgkmcnt(0)
	v_fmac_f32_e32 v5, v6, v6
	v_add_u32_e32 v6, 44, v3
	v_and_b32_e32 v6, 63, v6
	v_lshl_add_u32 v6, v6, 2, v4
	ds_read_b32 v6, v6
	s_waitcnt lgkmcnt(0)
	v_fmac_f32_e32 v5, v6, v6
	v_add_u32_e32 v6, 45, v3
	v_and_b32_e32 v6, 63, v6
	v_lshl_add_u32 v6, v6, 2, v4
	ds_read_b32 v6, v6
	s_waitcnt lgkmcnt(0)
	v_fmac_f32_e32 v5, v6, v6
	v_add_u32_e32 v6, 46, v3
	v_and_b32_e32 v6, 63, v6
	v_lshl_add_u32 v6, v6, 2, v4
	ds_read_b32 v6, v6
	s_waitcnt lgkmcnt(0)
	v_fmac_f32_e32 v5, v6, v6
	v_add_u32_e32 v6, 47, v3
	v_and_b32_e32 v6, 63, v6
	v_lshl_add_u32 v6, v6, 2, v4
	ds_read_b32 v6, v6
	s_waitcnt lgkmcnt(0)
	v_fmac_f32_e32 v5, v6, v6
	v_add_u32_e32 v6, 48, v3
	v_and_b32_e32 v6, 63, v6
	v_lshl_add_u32 v6, v6, 2, v4
	ds_read_b32 v6, v6
	s_waitcnt lgkmcnt(0)
	v_fmac_f32_e32 v5, v6, v6
	v_add_u32_e32 v6, 49, v3
	v_and_b32_e32 v6, 63, v6
	v_lshl_add_u32 v6, v6, 2, v4
	ds_read_b32 v6, v6
	s_waitcnt lgkmcnt(0)
	v_fmac_f32_e32 v5, v6, v6
	v_add_u32_e32 v6, 50, v3
	v_and_b32_e32 v6, 63, v6
	v_lshl_add_u32 v6, v6, 2, v4
	ds_read_b32 v6, v6
	s_waitcnt lgkmcnt(0)
	v_fmac_f32_e32 v5, v6, v6
	v_add_u32_e32 v6, 51, v3
	v_and_b32_e32 v6, 63, v6
	v_lshl_add_u32 v6, v6, 2, v4
	ds_read_b32 v6, v6
	s_waitcnt lgkmcnt(0)
	v_fmac_f32_e32 v5, v6, v6
	v_add_u32_e32 v6, 52, v3
	v_and_b32_e32 v6, 63, v6
	v_lshl_add_u32 v6, v6, 2, v4
	ds_read_b32 v6, v6
	s_waitcnt lgkmcnt(0)
	v_fmac_f32_e32 v5, v6, v6
	v_add_u32_e32 v6, 53, v3
	v_and_b32_e32 v6, 63, v6
	v_lshl_add_u32 v6, v6, 2, v4
	ds_read_b32 v6, v6
	s_waitcnt lgkmcnt(0)
	v_fmac_f32_e32 v5, v6, v6
	v_add_u32_e32 v6, 54, v3
	v_and_b32_e32 v6, 63, v6
	v_lshl_add_u32 v6, v6, 2, v4
	ds_read_b32 v6, v6
	s_waitcnt lgkmcnt(0)
	v_pk_mul_f32 v[6:7], v[6:7], v[6:7]
	s_nop 0
	v_add_f32_e32 v5, v5, v6
	v_add_f32_e32 v5, v5, v7
	v_add_u32_e32 v6, 56, v3
	v_add_u32_e32 v7, 57, v3
	v_and_b32_e32 v6, 63, v6
	v_and_b32_e32 v7, 63, v7
	v_lshl_add_u32 v6, v6, 2, v4
	v_lshl_add_u32 v7, v7, 2, v4
	ds_read_b32 v6, v6
	ds_read_b32 v7, v7
	s_waitcnt lgkmcnt(0)
	v_pk_mul_f32 v[6:7], v[6:7], v[6:7]
	s_nop 0
	v_add_f32_e32 v5, v5, v6
	v_add_f32_e32 v5, v5, v7
	v_add_u32_e32 v6, 58, v3
	v_add_u32_e32 v7, 59, v3
	v_and_b32_e32 v6, 63, v6
	v_and_b32_e32 v7, 63, v7
	v_lshl_add_u32 v6, v6, 2, v4
	v_lshl_add_u32 v7, v7, 2, v4
	ds_read_b32 v6, v6
	ds_read_b32 v7, v7
	s_waitcnt lgkmcnt(0)
	v_pk_mul_f32 v[6:7], v[6:7], v[6:7]
	s_nop 0
	v_add_f32_e32 v5, v5, v6
	v_add_f32_e32 v5, v5, v7
	v_add_u32_e32 v6, 60, v3
	v_add_u32_e32 v7, 61, v3
	v_and_b32_e32 v6, 63, v6
	v_and_b32_e32 v7, 63, v7
	v_lshl_add_u32 v6, v6, 2, v4
	v_lshl_add_u32 v7, v7, 2, v4
	ds_read_b32 v6, v6
	ds_read_b32 v7, v7
	s_waitcnt lgkmcnt(0)
	v_pk_mul_f32 v[6:7], v[6:7], v[6:7]
	s_nop 0
	v_add_f32_e32 v5, v5, v6
	v_add_f32_e32 v8, v5, v7
	v_add_u32_e32 v5, 62, v3
	v_add_u32_e32 v3, -1, v3
	v_and_b32_e32 v5, 63, v5
	v_and_b32_e32 v3, 63, v3
	v_lshl_add_u32 v5, v5, 2, v4
	v_lshl_add_u32 v3, v3, 2, v4
	ds_read_b32 v6, v5
	ds_read_b32 v7, v3
	s_waitcnt lgkmcnt(0)
	v_pk_mul_f32 v[4:5], v[6:7], v[6:7]
	s_nop 0
	v_add_f32_e32 v3, v8, v4
	v_add_f32_e32 v3, v3, v5
	v_fmamk_f32 v3, v3, 0x3c800000, v231
	v_cmp_gt_f32_e32 vcc, s0, v3
	v_mul_f32_e32 v4, 0x4b800000, v3
	s_mov_b32 s0, 0x3ffffffe
	v_cndmask_b32_e32 v3, v3, v4, vcc
	v_rsq_f32_e32 v3, v3
	v_and_or_b32 v0, v0, s0, v2
	v_lshl_add_u32 v0, v0, 2, v237
	v_mul_f32_e32 v4, 0x45800000, v3
	v_cndmask_b32_e32 v3, v3, v4, vcc
	ds_write_b32 v0, v3
	v_mov_b32_e32 v0, v230
	s_waitcnt lgkmcnt(0)
	s_barrier
; #define TIDX (tid_launder())
; DI unsigned pack2(float a, float b) { hwf2 v = {a, b}; hwbf2 r = __builtin_convertvector(v, hwbf2); return __builtin_bit_cast(unsigned, r); }
; DI float siluf(float x) { return x * __builtin_amdgcn_rcpf(1.f + __expf(-x)); }
; DI void epi_store64(const float* Ct, int cb, const float* rn, int grp, const float* gain, bool silu, const float* bias,
;                     bf16_t* dst, size_t ldd, int dcol0, int m0, int Mmax) {
;   const int tid = TIDX, c = (tid & 15) * 4;
;   float4 gv = make_float4(1.f, 1.f, 1.f, 1.f), bv = make_float4(0.f, 0.f, 0.f, 0.f);
;   if (rn) gv = *(const float4*)(gain + c);
;   if (bias) bv = *(const float4*)(bias + c);
; #pragma unroll
;   for (int q = 0; q < 8; ++q) {
;     const int row = (tid >> 4) + 16 * q;
;     float4 v = *(const float4*)(Ct + row * 132 + cb + c);
;     v.x += bv.x; v.y += bv.y; v.z += bv.z; v.w += bv.w;
;     if (rn) { const float sc = rn[row * 2 + grp]; v.x *= sc * gv.x; v.y *= sc * gv.y; v.z *= sc * gv.z; v.w *= sc * gv.w; }
;     if (silu) { v.x = siluf(v.x); v.y = siluf(v.y); v.z = siluf(v.z); v.w = siluf(v.w); }
;     uint2 o; o.x = pack2(v.x, v.y); o.y = pack2(v.z, v.w);
;     *(uint2*)(dst + (size_t)(m0 + row) * ldd + dcol0 + c) = o;
;   }
; }
	s_andn2_b64 vcc, exec, s[6:7]
	v_lshlrev_b32_e32 v2, 2, v0
	v_and_b32_e32 v4, 60, v2
	v_ashrrev_i32_e32 v8, 4, v0
	v_lshlrev_b32_e32 v0, 1, v4
	v_lshl_add_u64 v[2:3], s[24:25], 0, v[0:1]
	v_mul_lo_u32 v0, v8, s79
	v_lshl_add_u32 v0, v4, 2, v0
	ds_read_b128 v[72:75], v0
	ds_read_b128 v[76:79], v0 offset:8448
	ds_read_b128 v[80:83], v0 offset:16896
	ds_read_b128 v[84:87], v0 offset:25344
	ds_read_b128 v[88:91], v0 offset:33792
	ds_read_b128 v[92:95], v0 offset:42240
	ds_read_b128 v[96:99], v0 offset:50688
	ds_read_b128 v[100:103], v0 offset:59136
	v_add_u32_e32 v8, s11, v8
	s_waitcnt lgkmcnt(7)
	v_pk_add_f32 v[4:5], v[72:73], 0 op_sel_hi:[1, 0]
	v_pk_add_f32 v[6:7], v[74:75], 0 op_sel_hi:[1, 0]
	v_cvt_pk_bf16_f32 v4, v4, v5
	v_cvt_pk_bf16_f32 v5, v6, v7
	v_mad_i64_i32 v[6:7], s[0:1], v8, s50, v[2:3]
	global_store_dwordx2 v[6:7], v[4:5], off offset:2560
	s_waitcnt lgkmcnt(6)
	v_pk_add_f32 v[4:5], v[76:77], 0 op_sel_hi:[1, 0]
	v_pk_add_f32 v[6:7], v[78:79], 0 op_sel_hi:[1, 0]
	v_cvt_pk_bf16_f32 v4, v4, v5
	v_cvt_pk_bf16_f32 v5, v6, v7
	v_add_u32_e32 v6, 16, v8
	v_mad_i64_i32 v[6:7], s[0:1], v6, s50, v[2:3]
	global_store_dwordx2 v[6:7], v[4:5], off offset:2560
	s_waitcnt lgkmcnt(5)
	v_pk_add_f32 v[4:5], v[80:81], 0 op_sel_hi:[1, 0]
	v_pk_add_f32 v[6:7], v[82:83], 0 op_sel_hi:[1, 0]
	v_cvt_pk_bf16_f32 v4, v4, v5
	v_cvt_pk_bf16_f32 v5, v6, v7
	v_add_u32_e32 v6, 32, v8
	v_mad_i64_i32 v[6:7], s[0:1], v6, s50, v[2:3]
	global_store_dwordx2 v[6:7], v[4:5], off offset:2560
	s_waitcnt lgkmcnt(4)
	v_pk_add_f32 v[4:5], v[84:85], 0 op_sel_hi:[1, 0]
	v_pk_add_f32 v[6:7], v[86:87], 0 op_sel_hi:[1, 0]
	v_cvt_pk_bf16_f32 v4, v4, v5
	v_cvt_pk_bf16_f32 v5, v6, v7
	v_add_u32_e32 v6, 48, v8
	v_mad_i64_i32 v[6:7], s[0:1], v6, s50, v[2:3]
	global_store_dwordx2 v[6:7], v[4:5], off offset:2560
	s_waitcnt lgkmcnt(3)
	v_pk_add_f32 v[4:5], v[88:89], 0 op_sel_hi:[1, 0]
	v_pk_add_f32 v[6:7], v[90:91], 0 op_sel_hi:[1, 0]
	v_cvt_pk_bf16_f32 v4, v4, v5
	v_cvt_pk_bf16_f32 v5, v6, v7
	v_add_u32_e32 v6, 64, v8
	v_mad_i64_i32 v[6:7], s[0:1], v6, s50, v[2:3]
	global_store_dwordx2 v[6:7], v[4:5], off offset:2560
	s_waitcnt lgkmcnt(2)
	v_pk_add_f32 v[4:5], v[92:93], 0 op_sel_hi:[1, 0]
	v_pk_add_f32 v[6:7], v[94:95], 0 op_sel_hi:[1, 0]
	v_cvt_pk_bf16_f32 v4, v4, v5
	v_cvt_pk_bf16_f32 v5, v6, v7
	v_add_u32_e32 v6, 0x50, v8
	v_mad_i64_i32 v[6:7], s[0:1], v6, s50, v[2:3]
	global_store_dwordx2 v[6:7], v[4:5], off offset:2560
	s_waitcnt lgkmcnt(1)
	v_pk_add_f32 v[4:5], v[96:97], 0 op_sel_hi:[1, 0]
	v_pk_add_f32 v[6:7], v[98:99], 0 op_sel_hi:[1, 0]
	v_cvt_pk_bf16_f32 v4, v4, v5
	v_cvt_pk_bf16_f32 v5, v6, v7
	v_add_u32_e32 v6, 0x60, v8
	v_mad_i64_i32 v[6:7], s[0:1], v6, s50, v[2:3]
	global_store_dwordx2 v[6:7], v[4:5], off offset:2560
	v_add_u32_e32 v0, 0x70, v8
	v_mad_i64_i32 v[2:3], s[0:1], v0, s50, v[2:3]
	s_waitcnt lgkmcnt(0)
	v_pk_add_f32 v[4:5], v[100:101], 0 op_sel_hi:[1, 0]
	v_pk_add_f32 v[6:7], v[102:103], 0 op_sel_hi:[1, 0]
	v_cvt_pk_bf16_f32 v4, v4, v5
	v_cvt_pk_bf16_f32 v5, v6, v7
	global_store_dwordx2 v[2:3], v[4:5], off offset:2560
	v_cndmask_b32_e64 v3, 0, 1, s[6:7]
	v_ashrrev_i32_e32 v0, 2, v18
	v_and_b32_e32 v2, -8, v0
	v_cmp_ne_u32_e64 s[0:1], 1, v3
	v_ashrrev_i32_e32 v3, 31, v2
	s_cbranch_vccnz .LBB0_2016
	v_readlane_b32 s6, v254, 7
	v_readlane_b32 s7, v254, 8
	s_nop 1
	v_lshl_add_u64 v[4:5], v[2:3], 2, s[6:7]
	global_load_dword v10, v[4:5], off offset:256

; #define TIDX (tid_launder())
; DI unsigned pack2(float a, float b) { hwf2 v = {a, b}; hwbf2 r = __builtin_convertvector(v, hwbf2); return __builtin_bit_cast(unsigned, r); }
; DI float siluf(float x) { return x * __builtin_amdgcn_rcpf(1.f + __expf(-x)); }
; DI void epi_store64(const float* Ct, int cb, const float* rn, int grp, const float* gain, bool silu, const float* bias,
;                     bf16_t* dst, size_t ldd, int dcol0, int m0, int Mmax) {
;   const int tid = TIDX, c = (tid & 15) * 4;
;   float4 gv = make_float4(1.f, 1.f, 1.f, 1.f), bv = make_float4(0.f, 0.f, 0.f, 0.f);
;   if (rn) gv = *(const float4*)(gain + c);
;   if (bias) bv = *(const float4*)(bias + c);
; #pragma unroll
;   for (int q = 0; q < 8; ++q) {
;     const int row = (tid >> 4) + 16 * q;
;     float4 v = *(const float4*)(Ct + row * 132 + cb + c);
;     v.x += bv.x; v.y += bv.y; v.z += bv.z; v.w += bv.w;
;     if (rn) { const float sc = rn[row * 2 + grp]; v.x *= sc * gv.x; v.y *= sc * gv.y; v.z *= sc * gv.z; v.w *= sc * gv.w; }
;     if (silu) { v.x = siluf(v.x); v.y = siluf(v.y); v.z = siluf(v.z); v.w = siluf(v.w); }
;     uint2 o; o.x = pack2(v.x, v.y); o.y = pack2(v.z, v.w);
;     *(uint2*)(dst + (size_t)(m0 + row) * ldd + dcol0 + c) = o;
;   }
; }
; DI void epi_storeKF(const float* Ct, int cb, const float* rn, int grp, const float* gain, bf16_t* dst) {
;   const int slot = TIDX, r = slot & 31, d0 = (slot >> 5) * 8;
;   float gq[8];
; #pragma unroll
;   for (int j = 0; j < 8; ++j) gq[j] = rn ? gain[d0 + j] : 1.f;
; #pragma unroll
;   for (int kt4 = 0; kt4 < 4; ++kt4) {
;     const int row = kt4 * 32 + r;
;     float v[8];
;     {
;       const float4 va = *(const float4*)(Ct + row * 132 + cb + d0), vb = *(const float4*)(Ct + row * 132 + cb + d0 + 4);
;       v[0] = va.x; v[1] = va.y; v[2] = va.z; v[3] = va.w; v[4] = vb.x; v[5] = vb.y; v[6] = vb.z; v[7] = vb.w;
;     }
;     if (rn) { const float sc = rn[row * 2 + grp];
; #pragma unroll
;       for (int j = 0; j < 8; ++j) v[j] *= sc * gq[j]; }
;     uint4 o; o.x = pack2(v[0], v[1]); o.y = pack2(v[2], v[3]); o.z = pack2(v[4], v[5]); o.w = pack2(v[6], v[7]);
;     *(uint4*)(dst + kt4 * 2048 + slot * 8) = o;
;   }
; }
.LBB0_2039:
	s_and_b64 vcc, exec, s[0:1]
	s_cbranch_vccz .LBB0_2041
	s_ashr_i32 s5, s4, 31
	s_ashr_i32 s0, s13, 5
	v_readlane_b32 s16, v253, 11
	s_ashr_i32 s1, s0, 31
	s_lshl_b64 s[4:5], s[4:5], 18
	v_readlane_b32 s18, v253, 13
	v_readlane_b32 s19, v253, 14
	s_add_u32 s3, s18, s4
	s_addc_u32 s4, s19, s5
	s_lshl_b64 s[0:1], s[0:1], 12
	v_mov_b32_e32 v0, v230
	s_add_u32 s0, s3, s0
	s_addc_u32 s1, s4, s1
	v_and_b32_e32 v4, 31, v0
	v_and_b32_e32 v5, 0xffffffe0, v0
	v_lshlrev_b32_e32 v2, 3, v0
	v_ashrrev_i32_e32 v3, 31, v2
	v_mad_u32_u24 v0, v4, s79, v5
	s_waitcnt vmcnt(4)
	v_lshl_add_u64 v[10:11], v[2:3], 1, s[0:1]
	ds_read_b128 v[2:5], v0
	ds_read_b128 v[6:9], v0 offset:16
	v_add_co_u32_e32 v12, vcc, s80, v10
	v_readlane_b32 s17, v253, 12
	s_waitcnt lgkmcnt(1)
	v_cvt_pk_bf16_f32 v2, v2, v3
	v_cvt_pk_bf16_f32 v3, v4, v5
	s_waitcnt lgkmcnt(0)
	v_cvt_pk_bf16_f32 v4, v6, v7
	v_cvt_pk_bf16_f32 v5, v8, v9
	global_store_dwordx4 v[10:11], v[2:5], off
	ds_read_b128 v[2:5], v0 offset:16896
	ds_read_b128 v[6:9], v0 offset:16912
	v_addc_co_u32_e32 v13, vcc, 0, v11, vcc
	v_readlane_b32 s20, v253, 15
	s_waitcnt lgkmcnt(1)
	v_cvt_pk_bf16_f32 v2, v2, v3
	v_cvt_pk_bf16_f32 v3, v4, v5
	s_waitcnt lgkmcnt(0)
	v_cvt_pk_bf16_f32 v4, v6, v7
	v_cvt_pk_bf16_f32 v5, v8, v9
	global_store_dwordx4 v[12:13], v[2:5], off offset:-4096
	ds_read_b128 v[2:5], v0 offset:33792
	ds_read_b128 v[6:9], v0 offset:33808
	v_readlane_b32 s21, v253, 16
	v_readlane_b32 s22, v253, 17
	v_readlane_b32 s23, v253, 18
	s_waitcnt lgkmcnt(1)
	v_cvt_pk_bf16_f32 v2, v2, v3
	v_cvt_pk_bf16_f32 v3, v4, v5
	s_waitcnt lgkmcnt(0)
	v_cvt_pk_bf16_f32 v4, v6, v7
	v_cvt_pk_bf16_f32 v5, v8, v9
	global_store_dwordx4 v[12:13], v[2:5], off
	ds_read_b128 v[2:5], v0 offset:50688
	ds_read_b128 v[6:9], v0 offset:50704
	v_mov_b32_e32 v0, v230
	v_readlane_b32 s24, v253, 19
	v_readlane_b32 s25, v253, 20
	s_waitcnt lgkmcnt(1)
	v_cvt_pk_bf16_f32 v2, v2, v3
	v_cvt_pk_bf16_f32 v3, v4, v5
	s_waitcnt lgkmcnt(0)
	v_cvt_pk_bf16_f32 v4, v6, v7
	v_add_co_u32_e32 v6, vcc, s81, v10
	v_cvt_pk_bf16_f32 v5, v8, v9
	s_nop 0
	v_addc_co_u32_e32 v7, vcc, 0, v11, vcc
	v_readlane_b32 s26, v253, 21
	v_readlane_b32 s27, v253, 22
	v_readlane_b32 s28, v253, 23
	v_readlane_b32 s29, v253, 24
	v_readlane_b32 s30, v253, 25
	v_readlane_b32 s31, v253, 26
	global_store_dwordx4 v[6:7], v[2:5], off
	v_readlane_b32 s16, v252, 57
	v_ashrrev_i32_e32 v8, 4, v0
	v_lshlrev_b32_e32 v2, 2, v0
	v_and_b32_e32 v4, 60, v2
	v_lshlrev_b32_e32 v0, 1, v4
	v_readlane_b32 s24, v253, 1
	v_readlane_b32 s25, v253, 2
	v_readlane_b32 s17, v252, 58
	v_readlane_b32 s18, v252, 59
	v_lshl_add_u64 v[2:3], s[24:25], 0, v[0:1]
	v_mul_lo_u32 v0, v8, s79
	v_lshl_add_u32 v0, v4, 2, v0
	ds_read_b128 v[72:75], v0 offset:256
	ds_read_b128 v[76:79], v0 offset:8704
	ds_read_b128 v[80:83], v0 offset:17152
	ds_read_b128 v[84:87], v0 offset:25600
	ds_read_b128 v[88:91], v0 offset:34048
	ds_read_b128 v[92:95], v0 offset:42496
	ds_read_b128 v[96:99], v0 offset:50944
	ds_read_b128 v[100:103], v0 offset:59392
	v_add_u32_e32 v8, s11, v8
	v_readlane_b32 s19, v252, 60
	v_readlane_b32 s20, v252, 61
	v_readlane_b32 s21, v252, 62
	s_waitcnt lgkmcnt(7)
	v_pk_add_f32 v[4:5], v[72:73], 0 op_sel_hi:[1, 0]
	v_pk_add_f32 v[6:7], v[74:75], 0 op_sel_hi:[1, 0]
	v_cvt_pk_bf16_f32 v4, v4, v5
	v_cvt_pk_bf16_f32 v5, v6, v7
	v_mad_i64_i32 v[6:7], s[0:1], v8, s50, v[2:3]
	global_store_dwordx2 v[6:7], v[4:5], off offset:2432
	v_readlane_b32 s22, v252, 63
	v_readlane_b32 s23, v253, 0
	v_readlane_b32 s26, v253, 3
	v_readlane_b32 s27, v253, 4
	s_waitcnt lgkmcnt(6)
	v_pk_add_f32 v[4:5], v[76:77], 0 op_sel_hi:[1, 0]
	v_pk_add_f32 v[6:7], v[78:79], 0 op_sel_hi:[1, 0]
	v_cvt_pk_bf16_f32 v4, v4, v5
	v_cvt_pk_bf16_f32 v5, v6, v7
	v_add_u32_e32 v6, 16, v8
	v_mad_i64_i32 v[6:7], s[0:1], v6, s50, v[2:3]
	global_store_dwordx2 v[6:7], v[4:5], off offset:2432
	v_readlane_b32 s28, v253, 5
	v_readlane_b32 s29, v253, 6
	v_readlane_b32 s30, v253, 7
	v_readlane_b32 s31, v253, 8
	s_waitcnt lgkmcnt(5)
	v_pk_add_f32 v[4:5], v[80:81], 0 op_sel_hi:[1, 0]
	v_pk_add_f32 v[6:7], v[82:83], 0 op_sel_hi:[1, 0]
	v_cvt_pk_bf16_f32 v4, v4, v5
	v_cvt_pk_bf16_f32 v5, v6, v7
	v_add_u32_e32 v6, 32, v8
	v_mad_i64_i32 v[6:7], s[0:1], v6, s50, v[2:3]
	global_store_dwordx2 v[6:7], v[4:5], off offset:2432
	s_waitcnt lgkmcnt(4)
	v_pk_add_f32 v[4:5], v[84:85], 0 op_sel_hi:[1, 0]
	v_pk_add_f32 v[6:7], v[86:87], 0 op_sel_hi:[1, 0]
	v_cvt_pk_bf16_f32 v4, v4, v5
	v_cvt_pk_bf16_f32 v5, v6, v7
	v_add_u32_e32 v6, 48, v8
	v_mad_i64_i32 v[6:7], s[0:1], v6, s50, v[2:3]
	global_store_dwordx2 v[6:7], v[4:5], off offset:2432
	s_waitcnt lgkmcnt(3)
	v_pk_add_f32 v[4:5], v[88:89], 0 op_sel_hi:[1, 0]
	v_pk_add_f32 v[6:7], v[90:91], 0 op_sel_hi:[1, 0]
	v_cvt_pk_bf16_f32 v4, v4, v5
	v_cvt_pk_bf16_f32 v5, v6, v7
	v_add_u32_e32 v6, 64, v8
	v_mad_i64_i32 v[6:7], s[0:1], v6, s50, v[2:3]
	global_store_dwordx2 v[6:7], v[4:5], off offset:2432
	s_waitcnt lgkmcnt(2)
	v_pk_add_f32 v[4:5], v[92:93], 0 op_sel_hi:[1, 0]
	v_pk_add_f32 v[6:7], v[94:95], 0 op_sel_hi:[1, 0]
	v_cvt_pk_bf16_f32 v4, v4, v5
	v_cvt_pk_bf16_f32 v5, v6, v7
	v_add_u32_e32 v6, 0x50, v8
	v_mad_i64_i32 v[6:7], s[0:1], v6, s50, v[2:3]
	global_store_dwordx2 v[6:7], v[4:5], off offset:2432
	s_waitcnt lgkmcnt(1)
	v_pk_add_f32 v[4:5], v[96:97], 0 op_sel_hi:[1, 0]
	v_pk_add_f32 v[6:7], v[98:99], 0 op_sel_hi:[1, 0]
	v_cvt_pk_bf16_f32 v4, v4, v5
	v_cvt_pk_bf16_f32 v5, v6, v7
	v_add_u32_e32 v6, 0x60, v8
	v_mad_i64_i32 v[6:7], s[0:1], v6, s50, v[2:3]
	global_store_dwordx2 v[6:7], v[4:5], off offset:2432
	v_add_u32_e32 v0, 0x70, v8
	v_mad_i64_i32 v[2:3], s[0:1], v0, s50, v[2:3]
	s_waitcnt lgkmcnt(0)
	v_pk_add_f32 v[4:5], v[100:101], 0 op_sel_hi:[1, 0]
	v_pk_add_f32 v[6:7], v[102:103], 0 op_sel_hi:[1, 0]
	v_cvt_pk_bf16_f32 v4, v4, v5
	v_cvt_pk_bf16_f32 v5, v6, v7
	global_store_dwordx2 v[2:3], v[4:5], off offset:2432

; #define TIDX (tid_launder())
; DI unsigned pack2(float a, float b) { hwf2 v = {a, b}; hwbf2 r = __builtin_convertvector(v, hwbf2); return __builtin_bit_cast(unsigned, r); }
; DI float siluf(float x) { return x * __builtin_amdgcn_rcpf(1.f + __expf(-x)); }
; DI void epi_store64(const float* Ct, int cb, const float* rn, int grp, const float* gain, bool silu, const float* bias,
;                     bf16_t* dst, size_t ldd, int dcol0, int m0, int Mmax) {
;   const int tid = TIDX, c = (tid & 15) * 4;
;   float4 gv = make_float4(1.f, 1.f, 1.f, 1.f), bv = make_float4(0.f, 0.f, 0.f, 0.f);
;   if (rn) gv = *(const float4*)(gain + c);
;   if (bias) bv = *(const float4*)(bias + c);
; #pragma unroll
;   for (int q = 0; q < 8; ++q) {
;     const int row = (tid >> 4) + 16 * q;
;     float4 v = *(const float4*)(Ct + row * 132 + cb + c);
;     v.x += bv.x; v.y += bv.y; v.z += bv.z; v.w += bv.w;
;     if (rn) { const float sc = rn[row * 2 + grp]; v.x *= sc * gv.x; v.y *= sc * gv.y; v.z *= sc * gv.z; v.w *= sc * gv.w; }
;     if (silu) { v.x = siluf(v.x); v.y = siluf(v.y); v.z = siluf(v.z); v.w = siluf(v.w); }
;     uint2 o; o.x = pack2(v.x, v.y); o.y = pack2(v.z, v.w);
;     *(uint2*)(dst + (size_t)(m0 + row) * ldd + dcol0 + c) = o;
;   }
; }
.LBB0_2042:
	s_and_b64 vcc, exec, s[0:1]
	s_cbranch_vccz .LBB0_2044
	v_mov_b32_e32 v0, v230
	s_mov_b32 s3, s15
	v_readlane_b32 s16, v252, 57
	s_lshl_b64 s[0:1], s[2:3], 1
	v_lshlrev_b32_e32 v2, 2, v0
	v_readlane_b32 s24, v253, 1
	v_and_b32_e32 v4, 60, v2
	v_readlane_b32 s25, v253, 2
	s_add_u32 s0, s24, s0
	v_ashrrev_i32_e32 v8, 4, v0
	s_addc_u32 s1, s25, s1
	v_lshlrev_b32_e32 v0, 1, v4
	v_lshl_add_u64 v[2:3], s[0:1], 0, v[0:1]
	v_mul_lo_u32 v0, v8, s79
	v_lshl_add_u32 v0, v4, 2, v0
	ds_read_b128 v[72:75], v0
	ds_read_b128 v[76:79], v0 offset:8448
	ds_read_b128 v[80:83], v0 offset:16896
	ds_read_b128 v[84:87], v0 offset:25344
	ds_read_b128 v[88:91], v0 offset:33792
	ds_read_b128 v[92:95], v0 offset:42240
	ds_read_b128 v[96:99], v0 offset:50688
	ds_read_b128 v[100:103], v0 offset:59136
	v_add_u32_e32 v8, s11, v8
	v_readlane_b32 s17, v252, 58
	v_readlane_b32 s18, v252, 59
	v_readlane_b32 s19, v252, 60
	s_waitcnt lgkmcnt(7)
	v_pk_add_f32 v[4:5], v[72:73], 0 op_sel_hi:[1, 0]
	v_pk_add_f32 v[6:7], v[74:75], 0 op_sel_hi:[1, 0]
	v_cvt_pk_bf16_f32 v4, v4, v5
	v_cvt_pk_bf16_f32 v5, v6, v7
	v_mad_i64_i32 v[6:7], s[4:5], v8, s50, v[2:3]
	global_store_dwordx2 v[6:7], v[4:5], off
	v_readlane_b32 s20, v252, 61
	v_readlane_b32 s21, v252, 62
	v_readlane_b32 s22, v252, 63
	v_readlane_b32 s23, v253, 0
	s_waitcnt lgkmcnt(6)
	v_pk_add_f32 v[4:5], v[76:77], 0 op_sel_hi:[1, 0]
	v_pk_add_f32 v[6:7], v[78:79], 0 op_sel_hi:[1, 0]
	v_cvt_pk_bf16_f32 v4, v4, v5
	v_cvt_pk_bf16_f32 v5, v6, v7
	v_add_u32_e32 v6, 16, v8
	v_mad_i64_i32 v[6:7], s[4:5], v6, s50, v[2:3]
	global_store_dwordx2 v[6:7], v[4:5], off
	v_readlane_b32 s26, v253, 3
	v_readlane_b32 s27, v253, 4
	v_readlane_b32 s28, v253, 5
	v_readlane_b32 s29, v253, 6
	s_waitcnt lgkmcnt(5)
	v_pk_add_f32 v[4:5], v[80:81], 0 op_sel_hi:[1, 0]
	v_pk_add_f32 v[6:7], v[82:83], 0 op_sel_hi:[1, 0]
	v_cvt_pk_bf16_f32 v4, v4, v5
	v_cvt_pk_bf16_f32 v5, v6, v7
	v_add_u32_e32 v6, 32, v8
	v_mad_i64_i32 v[6:7], s[4:5], v6, s50, v[2:3]
	global_store_dwordx2 v[6:7], v[4:5], off
	v_readlane_b32 s30, v253, 7
	v_readlane_b32 s31, v253, 8
	s_waitcnt lgkmcnt(4)
	v_pk_add_f32 v[4:5], v[84:85], 0 op_sel_hi:[1, 0]
	v_pk_add_f32 v[6:7], v[86:87], 0 op_sel_hi:[1, 0]
	v_cvt_pk_bf16_f32 v4, v4, v5
	v_cvt_pk_bf16_f32 v5, v6, v7
	v_add_u32_e32 v6, 48, v8
	v_mad_i64_i32 v[6:7], s[4:5], v6, s50, v[2:3]
	global_store_dwordx2 v[6:7], v[4:5], off
	s_waitcnt lgkmcnt(3)
	v_pk_add_f32 v[4:5], v[88:89], 0 op_sel_hi:[1, 0]
	v_pk_add_f32 v[6:7], v[90:91], 0 op_sel_hi:[1, 0]
	v_cvt_pk_bf16_f32 v4, v4, v5
	v_cvt_pk_bf16_f32 v5, v6, v7
	v_add_u32_e32 v6, 64, v8
	v_mad_i64_i32 v[6:7], s[4:5], v6, s50, v[2:3]
	global_store_dwordx2 v[6:7], v[4:5], off
	s_waitcnt lgkmcnt(2)
	v_pk_add_f32 v[4:5], v[92:93], 0 op_sel_hi:[1, 0]
	v_pk_add_f32 v[6:7], v[94:95], 0 op_sel_hi:[1, 0]
	v_cvt_pk_bf16_f32 v4, v4, v5
	v_cvt_pk_bf16_f32 v5, v6, v7
	v_add_u32_e32 v6, 0x50, v8
	v_mad_i64_i32 v[6:7], s[4:5], v6, s50, v[2:3]
	global_store_dwordx2 v[6:7], v[4:5], off
	s_waitcnt lgkmcnt(1)
	v_pk_add_f32 v[4:5], v[96:97], 0 op_sel_hi:[1, 0]
	v_pk_add_f32 v[6:7], v[98:99], 0 op_sel_hi:[1, 0]
	v_cvt_pk_bf16_f32 v4, v4, v5
	v_cvt_pk_bf16_f32 v5, v6, v7
	v_add_u32_e32 v6, 0x60, v8
	v_mad_i64_i32 v[6:7], s[4:5], v6, s50, v[2:3]
	global_store_dwordx2 v[6:7], v[4:5], off
	v_add_u32_e32 v0, 0x70, v8
	v_mad_i64_i32 v[2:3], s[4:5], v0, s50, v[2:3]
	v_mov_b32_e32 v0, v230
	s_waitcnt lgkmcnt(0)
	v_pk_add_f32 v[4:5], v[100:101], 0 op_sel_hi:[1, 0]
	v_pk_add_f32 v[6:7], v[102:103], 0 op_sel_hi:[1, 0]
	v_cvt_pk_bf16_f32 v4, v4, v5
	v_cvt_pk_bf16_f32 v5, v6, v7
	global_store_dwordx2 v[2:3], v[4:5], off
	s_nop 0
	v_lshlrev_b32_e32 v2, 2, v0
	v_and_b32_e32 v4, 60, v2
	v_ashrrev_i32_e32 v8, 4, v0
	v_lshlrev_b32_e32 v0, 1, v4
	v_lshl_add_u64 v[2:3], s[0:1], 0, v[0:1]
	v_mul_lo_u32 v0, v8, s79
	v_lshl_add_u32 v0, v4, 2, v0
	ds_read_b128 v[72:75], v0 offset:256
	ds_read_b128 v[76:79], v0 offset:8704
	ds_read_b128 v[80:83], v0 offset:17152
	ds_read_b128 v[84:87], v0 offset:25600
	ds_read_b128 v[88:91], v0 offset:34048
	ds_read_b128 v[92:95], v0 offset:42496
	ds_read_b128 v[96:99], v0 offset:50944
	ds_read_b128 v[100:103], v0 offset:59392
	v_add_u32_e32 v8, s11, v8
	s_waitcnt lgkmcnt(7)
	v_pk_add_f32 v[4:5], v[72:73], 0 op_sel_hi:[1, 0]
	v_pk_add_f32 v[6:7], v[74:75], 0 op_sel_hi:[1, 0]
	v_cvt_pk_bf16_f32 v4, v4, v5
	v_cvt_pk_bf16_f32 v5, v6, v7
	v_mad_i64_i32 v[6:7], s[0:1], v8, s50, v[2:3]
	global_store_dwordx2 v[6:7], v[4:5], off offset:128
	s_waitcnt lgkmcnt(6)
	v_pk_add_f32 v[4:5], v[76:77], 0 op_sel_hi:[1, 0]
	v_pk_add_f32 v[6:7], v[78:79], 0 op_sel_hi:[1, 0]
	v_cvt_pk_bf16_f32 v4, v4, v5
	v_cvt_pk_bf16_f32 v5, v6, v7
	v_add_u32_e32 v6, 16, v8
	v_mad_i64_i32 v[6:7], s[0:1], v6, s50, v[2:3]
	global_store_dwordx2 v[6:7], v[4:5], off offset:128
	s_waitcnt lgkmcnt(5)
	v_pk_add_f32 v[4:5], v[80:81], 0 op_sel_hi:[1, 0]
	v_pk_add_f32 v[6:7], v[82:83], 0 op_sel_hi:[1, 0]
	v_cvt_pk_bf16_f32 v4, v4, v5
	v_cvt_pk_bf16_f32 v5, v6, v7
	v_add_u32_e32 v6, 32, v8
	v_mad_i64_i32 v[6:7], s[0:1], v6, s50, v[2:3]
	global_store_dwordx2 v[6:7], v[4:5], off offset:128
	s_waitcnt lgkmcnt(4)
	v_pk_add_f32 v[4:5], v[84:85], 0 op_sel_hi:[1, 0]
	v_pk_add_f32 v[6:7], v[86:87], 0 op_sel_hi:[1, 0]
	v_cvt_pk_bf16_f32 v4, v4, v5
	v_cvt_pk_bf16_f32 v5, v6, v7
	v_add_u32_e32 v6, 48, v8
	v_mad_i64_i32 v[6:7], s[0:1], v6, s50, v[2:3]
	global_store_dwordx2 v[6:7], v[4:5], off offset:128
	s_waitcnt lgkmcnt(3)
	v_pk_add_f32 v[4:5], v[88:89], 0 op_sel_hi:[1, 0]
	v_pk_add_f32 v[6:7], v[90:91], 0 op_sel_hi:[1, 0]
	v_cvt_pk_bf16_f32 v4, v4, v5
	v_cvt_pk_bf16_f32 v5, v6, v7
	v_add_u32_e32 v6, 64, v8
	v_mad_i64_i32 v[6:7], s[0:1], v6, s50, v[2:3]
	global_store_dwordx2 v[6:7], v[4:5], off offset:128
	s_waitcnt lgkmcnt(2)
	v_pk_add_f32 v[4:5], v[92:93], 0 op_sel_hi:[1, 0]
	v_pk_add_f32 v[6:7], v[94:95], 0 op_sel_hi:[1, 0]
	v_cvt_pk_bf16_f32 v4, v4, v5
	v_cvt_pk_bf16_f32 v5, v6, v7
	v_add_u32_e32 v6, 0x50, v8
	v_mad_i64_i32 v[6:7], s[0:1], v6, s50, v[2:3]
	global_store_dwordx2 v[6:7], v[4:5], off offset:128
	s_waitcnt lgkmcnt(1)
	v_pk_add_f32 v[4:5], v[96:97], 0 op_sel_hi:[1, 0]
	v_pk_add_f32 v[6:7], v[98:99], 0 op_sel_hi:[1, 0]
	v_cvt_pk_bf16_f32 v4, v4, v5
	v_cvt_pk_bf16_f32 v5, v6, v7
	v_add_u32_e32 v6, 0x60, v8
	v_mad_i64_i32 v[6:7], s[0:1], v6, s50, v[2:3]
	global_store_dwordx2 v[6:7], v[4:5], off offset:128
	v_add_u32_e32 v0, 0x70, v8
	v_mad_i64_i32 v[2:3], s[0:1], v0, s50, v[2:3]
	s_waitcnt lgkmcnt(0)
	v_pk_add_f32 v[4:5], v[100:101], 0 op_sel_hi:[1, 0]
	v_pk_add_f32 v[6:7], v[102:103], 0 op_sel_hi:[1, 0]
	v_cvt_pk_bf16_f32 v4, v4, v5
	v_cvt_pk_bf16_f32 v5, v6, v7
	global_store_dwordx2 v[2:3], v[4:5], off offset:128

; #define TIDX (tid_launder())
; DI void epi_rownorm(const float* Ct, float* rn, int W) {
;   const int row = TIDX >> 1, grp = TIDX & 1;
;   float ss = 0.f;
;   for (int c0 = 0; c0 < 64; ++c0) { const int c = (c0 + row) & 63; const float v = Ct[row * 132 + grp * 64 + c]; ss += v * v; }
;   if (W == 128) { ss += __shfl_xor(ss, 1); ss *= 0.5f; }
;   rn[row * 2 + grp] = rsqrtf(ss * (1.f / 64.f) + 1e-6f);
.LBB0_2199:
	s_and_b64 vcc, exec, s[0:1]
	s_cbranch_vccz .LBB0_2228
	s_cmp_gt_i32 s68, -3
	s_mov_b64 s[0:1], -1
	s_cbranch_scc0 .LBB0_2226
	v_mov_b32_e32 v0, v230
	v_mov_b32_e32 v2, v230
	s_mov_b32 s0, 0x800000
	v_ashrrev_i32_e32 v3, 1, v0
	v_and_b32_e32 v2, 1, v2
	v_mul_lo_u32 v4, v3, s79
	v_add_u32_e32 v7, 55, v3
	v_lshl_add_u32 v4, v2, 8, v4
	v_and_b32_e32 v5, 63, v3
	v_and_b32_e32 v7, 63, v7
	v_lshl_add_u32 v5, v5, 2, v4
	v_lshl_add_u32 v7, v7, 2, v4
	ds_read_b32 v6, v5
	ds_read_b32 v7, v7
	v_add_u32_e32 v5, 1, v3
	v_and_b32_e32 v5, 63, v5
	v_lshl_add_u32 v5, v5, 2, v4
	ds_read_b32 v5, v5
	v_readlane_b32 s16, v252, 57
	v_readlane_b32 s24, v253, 1
	v_readlane_b32 s25, v253, 2
	v_mov_b32_e32 v18, v230
	s_waitcnt lgkmcnt(0)
	v_mul_f32_e32 v5, v5, v5
	v_fmac_f32_e32 v5, v6, v6
	v_add_u32_e32 v6, 2, v3
	v_and_b32_e32 v6, 63, v6
	v_lshl_add_u32 v6, v6, 2, v4
	ds_read_b32 v6, v6
	s_mov_b64 s[6:7], -1
	s_waitcnt vmcnt(4)
	v_mov_b32_e32 v11, 1.0
	v_mov_b32_e32 v10, 1.0
	v_readlane_b32 s17, v252, 58
	s_waitcnt lgkmcnt(0)
	v_fmac_f32_e32 v5, v6, v6
	v_add_u32_e32 v6, 3, v3
	v_and_b32_e32 v6, 63, v6
	v_lshl_add_u32 v6, v6, 2, v4
	ds_read_b32 v6, v6
	v_readlane_b32 s18, v252, 59
	v_readlane_b32 s19, v252, 60
	v_readlane_b32 s20, v252, 61
	v_readlane_b32 s21, v252, 62
	s_waitcnt lgkmcnt(0)
	v_fmac_f32_e32 v5, v6, v6
	v_add_u32_e32 v6, 4, v3
	v_and_b32_e32 v6, 63, v6
	v_lshl_add_u32 v6, v6, 2, v4
	ds_read_b32 v6, v6
	v_readlane_b32 s22, v252, 63
	v_readlane_b32 s23, v253, 0
	v_readlane_b32 s26, v253, 3
	v_readlane_b32 s27, v253, 4
	s_waitcnt lgkmcnt(0)
	v_fmac_f32_e32 v5, v6, v6
	v_add_u32_e32 v6, 5, v3
	v_and_b32_e32 v6, 63, v6
	v_lshl_add_u32 v6, v6, 2, v4
	ds_read_b32 v6, v6
	v_readlane_b32 s28, v253, 5
	v_readlane_b32 s29, v253, 6
	v_readlane_b32 s30, v253, 7
	v_readlane_b32 s31, v253, 8
	s_waitcnt lgkmcnt(0)
	v_fmac_f32_e32 v5, v6, v6
	v_add_u32_e32 v6, 6, v3
	v_and_b32_e32 v6, 63, v6
	v_lshl_add_u32 v6, v6, 2, v4
	ds_read_b32 v6, v6
	s_waitcnt lgkmcnt(0)
	v_fmac_f32_e32 v5, v6, v6
	v_add_u32_e32 v6, 7, v3
	v_and_b32_e32 v6, 63, v6
	v_lshl_add_u32 v6, v6, 2, v4
	ds_read_b32 v6, v6
	s_waitcnt lgkmcnt(0)
	v_fmac_f32_e32 v5, v6, v6
	v_add_u32_e32 v6, 8, v3
	v_and_b32_e32 v6, 63, v6
	v_lshl_add_u32 v6, v6, 2, v4
	ds_read_b32 v6, v6
	s_waitcnt lgkmcnt(0)
	v_fmac_f32_e32 v5, v6, v6
	v_add_u32_e32 v6, 9, v3
	v_and_b32_e32 v6, 63, v6
	v_lshl_add_u32 v6, v6, 2, v4
	ds_read_b32 v6, v6
	s_waitcnt lgkmcnt(0)
	v_fmac_f32_e32 v5, v6, v6
	v_add_u32_e32 v6, 10, v3
	v_and_b32_e32 v6, 63, v6
	v_lshl_add_u32 v6, v6, 2, v4
	ds_read_b32 v6, v6
	s_waitcnt lgkmcnt(0)
	v_fmac_f32_e32 v5, v6, v6
	v_add_u32_e32 v6, 11, v3
	v_and_b32_e32 v6, 63, v6
	v_lshl_add_u32 v6, v6, 2, v4
	ds_read_b32 v6, v6
	s_waitcnt lgkmcnt(0)
	v_fmac_f32_e32 v5, v6, v6
	v_add_u32_e32 v6, 12, v3
	v_and_b32_e32 v6, 63, v6
	v_lshl_add_u32 v6, v6, 2, v4
	ds_read_b32 v6, v6
	s_waitcnt lgkmcnt(0)
	v_fmac_f32_e32 v5, v6, v6
	v_add_u32_e32 v6, 13, v3
	v_and_b32_e32 v6, 63, v6
	v_lshl_add_u32 v6, v6, 2, v4
	ds_read_b32 v6, v6
	s_waitcnt lgkmcnt(0)
	v_fmac_f32_e32 v5, v6, v6
	v_add_u32_e32 v6, 14, v3
	v_and_b32_e32 v6, 63, v6
	v_lshl_add_u32 v6, v6, 2, v4
	ds_read_b32 v6, v6
	s_waitcnt lgkmcnt(0)
	v_fmac_f32_e32 v5, v6, v6
	v_add_u32_e32 v6, 15, v3
	v_and_b32_e32 v6, 63, v6
	v_lshl_add_u32 v6, v6, 2, v4
	ds_read_b32 v6, v6
	s_waitcnt lgkmcnt(0)
	v_fmac_f32_e32 v5, v6, v6
	v_add_u32_e32 v6, 16, v3
	v_and_b32_e32 v6, 63, v6
	v_lshl_add_u32 v6, v6, 2, v4
	ds_read_b32 v6, v6
	s_waitcnt lgkmcnt(0)
	v_fmac_f32_e32 v5, v6, v6
	v_add_u32_e32 v6, 17, v3
	v_and_b32_e32 v6, 63, v6
	v_lshl_add_u32 v6, v6, 2, v4
	ds_read_b32 v6, v6
	s_waitcnt lgkmcnt(0)
	v_fmac_f32_e32 v5, v6, v6
	v_add_u32_e32 v6, 18, v3
	v_and_b32_e32 v6, 63, v6
	v_lshl_add_u32 v6, v6, 2, v4
	ds_read_b32 v6, v6
	s_waitcnt lgkmcnt(0)
	v_fmac_f32_e32 v5, v6, v6
	v_add_u32_e32 v6, 19, v3
	v_and_b32_e32 v6, 63, v6
	v_lshl_add_u32 v6, v6, 2, v4
	ds_read_b32 v6, v6
	s_waitcnt lgkmcnt(0)
	v_fmac_f32_e32 v5, v6, v6
	v_add_u32_e32 v6, 20, v3
	v_and_b32_e32 v6, 63, v6
	v_lshl_add_u32 v6, v6, 2, v4
	ds_read_b32 v6, v6
	s_waitcnt lgkmcnt(0)
	v_fmac_f32_e32 v5, v6, v6
	v_add_u32_e32 v6, 21, v3
	v_and_b32_e32 v6, 63, v6
	v_lshl_add_u32 v6, v6, 2, v4
	ds_read_b32 v6, v6
	s_waitcnt lgkmcnt(0)
	v_fmac_f32_e32 v5, v6, v6
	v_add_u32_e32 v6, 22, v3
	v_and_b32_e32 v6, 63, v6
	v_lshl_add_u32 v6, v6, 2, v4
	ds_read_b32 v6, v6
	s_waitcnt lgkmcnt(0)
	v_fmac_f32_e32 v5, v6, v6
	v_add_u32_e32 v6, 23, v3
	v_and_b32_e32 v6, 63, v6
	v_lshl_add_u32 v6, v6, 2, v4
	ds_read_b32 v6, v6
	s_waitcnt lgkmcnt(0)
	v_fmac_f32_e32 v5, v6, v6
	v_add_u32_e32 v6, 24, v3
	v_and_b32_e32 v6, 63, v6
	v_lshl_add_u32 v6, v6, 2, v4
	ds_read_b32 v6, v6
	s_waitcnt lgkmcnt(0)
	v_fmac_f32_e32 v5, v6, v6
	v_add_u32_e32 v6, 25, v3
	v_and_b32_e32 v6, 63, v6
	v_lshl_add_u32 v6, v6, 2, v4
	ds_read_b32 v6, v6
	s_waitcnt lgkmcnt(0)
	v_fmac_f32_e32 v5, v6, v6
	v_add_u32_e32 v6, 26, v3
	v_and_b32_e32 v6, 63, v6
	v_lshl_add_u32 v6, v6, 2, v4
	ds_read_b32 v6, v6
	s_waitcnt lgkmcnt(0)
	v_fmac_f32_e32 v5, v6, v6
	v_add_u32_e32 v6, 27, v3
	v_and_b32_e32 v6, 63, v6
	v_lshl_add_u32 v6, v6, 2, v4
	ds_read_b32 v6, v6
	s_waitcnt lgkmcnt(0)
	v_fmac_f32_e32 v5, v6, v6
	v_add_u32_e32 v6, 28, v3
	v_and_b32_e32 v6, 63, v6
	v_lshl_add_u32 v6, v6, 2, v4
	ds_read_b32 v6, v6
	s_waitcnt lgkmcnt(0)
	v_fmac_f32_e32 v5, v6, v6
	v_add_u32_e32 v6, 29, v3
	v_and_b32_e32 v6, 63, v6
	v_lshl_add_u32 v6, v6, 2, v4
	ds_read_b32 v6, v6
	s_waitcnt lgkmcnt(0)
	v_fmac_f32_e32 v5, v6, v6
	v_add_u32_e32 v6, 30, v3
	v_and_b32_e32 v6, 63, v6
	v_lshl_add_u32 v6, v6, 2, v4
	ds_read_b32 v6, v6
	s_waitcnt lgkmcnt(0)
; DI void epi_rownorm(const float* Ct, float* rn, int W) {
;     ...
;   for (int c0 = 0; c0 < 64; ++c0) { const int c = (c0 + row) & 63; const float v = Ct[row * 132 + grp * 64 + c]; ss += v * v; }
;   if (W == 128) { ss += __shfl_xor(ss, 1); ss *= 0.5f; }
;   rn[row * 2 + grp] = rsqrtf(ss * (1.f / 64.f) + 1e-6f);
;   __syncthreads();
	v_fmac_f32_e32 v5, v6, v6
	v_add_u32_e32 v6, 31, v3
	v_and_b32_e32 v6, 63, v6
	v_lshl_add_u32 v6, v6, 2, v4
	ds_read_b32 v6, v6
	s_waitcnt lgkmcnt(0)
	v_fmac_f32_e32 v5, v6, v6
	v_bitop3_b32 v6, v3, 32, 63 bitop3:0x6c
	v_lshl_add_u32 v6, v6, 2, v4
	ds_read_b32 v6, v6
	s_waitcnt lgkmcnt(0)
	v_fmac_f32_e32 v5, v6, v6
	v_add_u32_e32 v6, 33, v3
	v_and_b32_e32 v6, 63, v6
	v_lshl_add_u32 v6, v6, 2, v4
	ds_read_b32 v6, v6
	s_waitcnt lgkmcnt(0)
	v_fmac_f32_e32 v5, v6, v6
	v_add_u32_e32 v6, 34, v3
	v_and_b32_e32 v6, 63, v6
	v_lshl_add_u32 v6, v6, 2, v4
	ds_read_b32 v6, v6
	s_waitcnt lgkmcnt(0)
	v_fmac_f32_e32 v5, v6, v6
	v_add_u32_e32 v6, 35, v3
	v_and_b32_e32 v6, 63, v6
	v_lshl_add_u32 v6, v6, 2, v4
	ds_read_b32 v6, v6
	s_waitcnt lgkmcnt(0)
	v_fmac_f32_e32 v5, v6, v6
	v_add_u32_e32 v6, 36, v3
	v_and_b32_e32 v6, 63, v6
	v_lshl_add_u32 v6, v6, 2, v4
	ds_read_b32 v6, v6
	s_waitcnt lgkmcnt(0)
	v_fmac_f32_e32 v5, v6, v6
	v_add_u32_e32 v6, 37, v3
	v_and_b32_e32 v6, 63, v6
	v_lshl_add_u32 v6, v6, 2, v4
	ds_read_b32 v6, v6
	s_waitcnt lgkmcnt(0)
	v_fmac_f32_e32 v5, v6, v6
	v_add_u32_e32 v6, 38, v3
	v_and_b32_e32 v6, 63, v6
	v_lshl_add_u32 v6, v6, 2, v4
	ds_read_b32 v6, v6
	s_waitcnt lgkmcnt(0)
	v_fmac_f32_e32 v5, v6, v6
	v_add_u32_e32 v6, 39, v3
	v_and_b32_e32 v6, 63, v6
	v_lshl_add_u32 v6, v6, 2, v4
	ds_read_b32 v6, v6
	s_waitcnt lgkmcnt(0)
	v_fmac_f32_e32 v5, v6, v6
	v_add_u32_e32 v6, 40, v3
	v_and_b32_e32 v6, 63, v6
	v_lshl_add_u32 v6, v6, 2, v4
	ds_read_b32 v6, v6
	s_waitcnt lgkmcnt(0)
	v_fmac_f32_e32 v5, v6, v6
	v_add_u32_e32 v6, 41, v3
	v_and_b32_e32 v6, 63, v6
	v_lshl_add_u32 v6, v6, 2, v4
	ds_read_b32 v6, v6
	s_waitcnt lgkmcnt(0)
	v_fmac_f32_e32 v5, v6, v6
	v_add_u32_e32 v6, 42, v3
	v_and_b32_e32 v6, 63, v6
	v_lshl_add_u32 v6, v6, 2, v4
	ds_read_b32 v6, v6
	s_waitcnt lgkmcnt(0)
	v_fmac_f32_e32 v5, v6, v6
	v_add_u32_e32 v6, 43, v3
	v_and_b32_e32 v6, 63, v6
	v_lshl_add_u32 v6, v6, 2, v4
	ds_read_b32 v6, v6
	s_waitcnt lgkmcnt(0)
	v_fmac_f32_e32 v5, v6, v6
	v_add_u32_e32 v6, 44, v3
	v_and_b32_e32 v6, 63, v6
	v_lshl_add_u32 v6, v6, 2, v4
	ds_read_b32 v6, v6
	s_waitcnt lgkmcnt(0)
	v_fmac_f32_e32 v5, v6, v6
	v_add_u32_e32 v6, 45, v3
	v_and_b32_e32 v6, 63, v6
	v_lshl_add_u32 v6, v6, 2, v4
	ds_read_b32 v6, v6
	s_waitcnt lgkmcnt(0)
	v_fmac_f32_e32 v5, v6, v6
	v_add_u32_e32 v6, 46, v3
	v_and_b32_e32 v6, 63, v6
	v_lshl_add_u32 v6, v6, 2, v4
	ds_read_b32 v6, v6
	s_waitcnt lgkmcnt(0)
	v_fmac_f32_e32 v5, v6, v6
	v_add_u32_e32 v6, 47, v3
	v_and_b32_e32 v6, 63, v6
	v_lshl_add_u32 v6, v6, 2, v4
	ds_read_b32 v6, v6
	s_waitcnt lgkmcnt(0)
	v_fmac_f32_e32 v5, v6, v6
	v_add_u32_e32 v6, 48, v3
	v_and_b32_e32 v6, 63, v6
	v_lshl_add_u32 v6, v6, 2, v4
	ds_read_b32 v6, v6
	s_waitcnt lgkmcnt(0)
	v_fmac_f32_e32 v5, v6, v6
	v_add_u32_e32 v6, 49, v3
	v_and_b32_e32 v6, 63, v6
	v_lshl_add_u32 v6, v6, 2, v4
	ds_read_b32 v6, v6
	s_waitcnt lgkmcnt(0)
	v_fmac_f32_e32 v5, v6, v6
	v_add_u32_e32 v6, 50, v3
	v_and_b32_e32 v6, 63, v6
	v_lshl_add_u32 v6, v6, 2, v4
	ds_read_b32 v6, v6
	s_waitcnt lgkmcnt(0)
	v_fmac_f32_e32 v5, v6, v6
	v_add_u32_e32 v6, 51, v3
	v_and_b32_e32 v6, 63, v6
	v_lshl_add_u32 v6, v6, 2, v4
	ds_read_b32 v6, v6
	s_waitcnt lgkmcnt(0)
	v_fmac_f32_e32 v5, v6, v6
	v_add_u32_e32 v6, 52, v3
	v_and_b32_e32 v6, 63, v6
	v_lshl_add_u32 v6, v6, 2, v4
	ds_read_b32 v6, v6
	s_waitcnt lgkmcnt(0)
	v_fmac_f32_e32 v5, v6, v6
	v_add_u32_e32 v6, 53, v3
	v_and_b32_e32 v6, 63, v6
	v_lshl_add_u32 v6, v6, 2, v4
	ds_read_b32 v6, v6
	s_waitcnt lgkmcnt(0)
	v_fmac_f32_e32 v5, v6, v6
	v_add_u32_e32 v6, 54, v3
	v_and_b32_e32 v6, 63, v6
	v_lshl_add_u32 v6, v6, 2, v4
	ds_read_b32 v6, v6
	s_waitcnt lgkmcnt(0)
	v_pk_mul_f32 v[6:7], v[6:7], v[6:7]
	s_nop 0
	v_add_f32_e32 v5, v5, v6
	v_add_f32_e32 v5, v5, v7
	v_add_u32_e32 v6, 56, v3
	v_add_u32_e32 v7, 57, v3
	v_and_b32_e32 v6, 63, v6
	v_and_b32_e32 v7, 63, v7
	v_lshl_add_u32 v6, v6, 2, v4
	v_lshl_add_u32 v7, v7, 2, v4
	ds_read_b32 v6, v6
	ds_read_b32 v7, v7
	s_waitcnt lgkmcnt(0)
	v_pk_mul_f32 v[6:7], v[6:7], v[6:7]
	s_nop 0
	v_add_f32_e32 v5, v5, v6
	v_add_f32_e32 v5, v5, v7
	v_add_u32_e32 v6, 58, v3
	v_add_u32_e32 v7, 59, v3
	v_and_b32_e32 v6, 63, v6
	v_and_b32_e32 v7, 63, v7
	v_lshl_add_u32 v6, v6, 2, v4
	v_lshl_add_u32 v7, v7, 2, v4
	ds_read_b32 v6, v6
	ds_read_b32 v7, v7
	s_waitcnt lgkmcnt(0)
	v_pk_mul_f32 v[6:7], v[6:7], v[6:7]
	s_nop 0
	v_add_f32_e32 v5, v5, v6
	v_add_f32_e32 v5, v5, v7
	v_add_u32_e32 v6, 60, v3
	v_add_u32_e32 v7, 61, v3
	v_and_b32_e32 v6, 63, v6
	v_and_b32_e32 v7, 63, v7
	v_lshl_add_u32 v6, v6, 2, v4
	v_lshl_add_u32 v7, v7, 2, v4
	ds_read_b32 v6, v6
	ds_read_b32 v7, v7
	s_waitcnt lgkmcnt(0)
	v_pk_mul_f32 v[6:7], v[6:7], v[6:7]
	s_nop 0
	v_add_f32_e32 v5, v5, v6
	v_add_f32_e32 v8, v5, v7
	v_add_u32_e32 v5, 62, v3
	v_add_u32_e32 v3, -1, v3
	v_and_b32_e32 v5, 63, v5
	v_and_b32_e32 v3, 63, v3
	v_lshl_add_u32 v5, v5, 2, v4
	v_lshl_add_u32 v3, v3, 2, v4
	ds_read_b32 v6, v5
	ds_read_b32 v7, v3
	s_waitcnt lgkmcnt(0)
	v_pk_mul_f32 v[4:5], v[6:7], v[6:7]
	s_nop 0
	v_add_f32_e32 v3, v8, v4
	v_add_f32_e32 v3, v3, v5
	v_fmamk_f32 v3, v3, 0x3c800000, v227
	v_cmp_gt_f32_e32 vcc, s0, v3
	v_mul_f32_e32 v4, 0x4b800000, v3
	s_mov_b32 s0, 0x3ffffffe
	v_cndmask_b32_e32 v3, v3, v4, vcc
	v_rsq_f32_e32 v3, v3
	v_and_or_b32 v0, v0, s0, v2
	v_lshl_add_u32 v0, v0, 2, v237
	v_mul_f32_e32 v4, 0x45800000, v3
	v_cndmask_b32_e32 v3, v3, v4, vcc
	ds_write_b32 v0, v3
	v_mov_b32_e32 v0, v230
	s_waitcnt lgkmcnt(0)
	s_barrier
; #define TIDX (tid_launder())
; DI unsigned pack2(float a, float b) { hwf2 v = {a, b}; hwbf2 r = __builtin_convertvector(v, hwbf2); return __builtin_bit_cast(unsigned, r); }
; DI float siluf(float x) { return x * __builtin_amdgcn_rcpf(1.f + __expf(-x)); }
; DI void epi_store64(const float* Ct, int cb, const float* rn, int grp, const float* gain, bool silu, const float* bias,
;                     bf16_t* dst, size_t ldd, int dcol0, int m0, int Mmax) {
;   const int tid = TIDX, c = (tid & 15) * 4;
;   float4 gv = make_float4(1.f, 1.f, 1.f, 1.f), bv = make_float4(0.f, 0.f, 0.f, 0.f);
;   if (rn) gv = *(const float4*)(gain + c);
;   if (bias) bv = *(const float4*)(bias + c);
; #pragma unroll
;   for (int q = 0; q < 8; ++q) {
;     const int row = (tid >> 4) + 16 * q;
;     float4 v = *(const float4*)(Ct + row * 132 + cb + c);
;     v.x += bv.x; v.y += bv.y; v.z += bv.z; v.w += bv.w;
;     if (rn) { const float sc = rn[row * 2 + grp]; v.x *= sc * gv.x; v.y *= sc * gv.y; v.z *= sc * gv.z; v.w *= sc * gv.w; }
;     if (silu) { v.x = siluf(v.x); v.y = siluf(v.y); v.z = siluf(v.z); v.w = siluf(v.w); }
;     uint2 o; o.x = pack2(v.x, v.y); o.y = pack2(v.z, v.w);
;     *(uint2*)(dst + (size_t)(m0 + row) * ldd + dcol0 + c) = o;
;   }
; }
	s_andn2_b64 vcc, exec, s[6:7]
	v_lshlrev_b32_e32 v2, 2, v0
	v_and_b32_e32 v4, 60, v2
	v_ashrrev_i32_e32 v8, 4, v0
	v_lshlrev_b32_e32 v0, 1, v4
	v_lshl_add_u64 v[2:3], s[24:25], 0, v[0:1]
	v_mul_lo_u32 v0, v8, s79
	v_lshl_add_u32 v0, v4, 2, v0
	ds_read_b128 v[72:75], v0
	ds_read_b128 v[76:79], v0 offset:8448
	ds_read_b128 v[80:83], v0 offset:16896
	ds_read_b128 v[84:87], v0 offset:25344
	ds_read_b128 v[88:91], v0 offset:33792
	ds_read_b128 v[92:95], v0 offset:42240
	ds_read_b128 v[96:99], v0 offset:50688
	ds_read_b128 v[100:103], v0 offset:59136
	v_add_u32_e32 v8, s13, v8
	s_waitcnt lgkmcnt(7)
	v_pk_add_f32 v[4:5], v[72:73], 0 op_sel_hi:[1, 0]
	v_pk_add_f32 v[6:7], v[74:75], 0 op_sel_hi:[1, 0]
	v_cvt_pk_bf16_f32 v4, v4, v5
	v_cvt_pk_bf16_f32 v5, v6, v7
	v_mad_i64_i32 v[6:7], s[0:1], v8, s50, v[2:3]
	global_store_dwordx2 v[6:7], v[4:5], off offset:2560
	s_waitcnt lgkmcnt(6)
	v_pk_add_f32 v[4:5], v[76:77], 0 op_sel_hi:[1, 0]
	v_pk_add_f32 v[6:7], v[78:79], 0 op_sel_hi:[1, 0]
	v_cvt_pk_bf16_f32 v4, v4, v5
	v_cvt_pk_bf16_f32 v5, v6, v7
	v_add_u32_e32 v6, 16, v8
	v_mad_i64_i32 v[6:7], s[0:1], v6, s50, v[2:3]
	global_store_dwordx2 v[6:7], v[4:5], off offset:2560
	s_waitcnt lgkmcnt(5)
	v_pk_add_f32 v[4:5], v[80:81], 0 op_sel_hi:[1, 0]
	v_pk_add_f32 v[6:7], v[82:83], 0 op_sel_hi:[1, 0]
	v_cvt_pk_bf16_f32 v4, v4, v5
	v_cvt_pk_bf16_f32 v5, v6, v7
	v_add_u32_e32 v6, 32, v8
	v_mad_i64_i32 v[6:7], s[0:1], v6, s50, v[2:3]
	global_store_dwordx2 v[6:7], v[4:5], off offset:2560
	s_waitcnt lgkmcnt(4)
	v_pk_add_f32 v[4:5], v[84:85], 0 op_sel_hi:[1, 0]
	v_pk_add_f32 v[6:7], v[86:87], 0 op_sel_hi:[1, 0]
	v_cvt_pk_bf16_f32 v4, v4, v5
	v_cvt_pk_bf16_f32 v5, v6, v7
	v_add_u32_e32 v6, 48, v8
	v_mad_i64_i32 v[6:7], s[0:1], v6, s50, v[2:3]
	global_store_dwordx2 v[6:7], v[4:5], off offset:2560
	s_waitcnt lgkmcnt(3)
	v_pk_add_f32 v[4:5], v[88:89], 0 op_sel_hi:[1, 0]
	v_pk_add_f32 v[6:7], v[90:91], 0 op_sel_hi:[1, 0]
	v_cvt_pk_bf16_f32 v4, v4, v5
	v_cvt_pk_bf16_f32 v5, v6, v7
	v_add_u32_e32 v6, 64, v8
	v_mad_i64_i32 v[6:7], s[0:1], v6, s50, v[2:3]
	global_store_dwordx2 v[6:7], v[4:5], off offset:2560
	s_waitcnt lgkmcnt(2)
	v_pk_add_f32 v[4:5], v[92:93], 0 op_sel_hi:[1, 0]
	v_pk_add_f32 v[6:7], v[94:95], 0 op_sel_hi:[1, 0]
	v_cvt_pk_bf16_f32 v4, v4, v5
	v_cvt_pk_bf16_f32 v5, v6, v7
	v_add_u32_e32 v6, 0x50, v8
	v_mad_i64_i32 v[6:7], s[0:1], v6, s50, v[2:3]
	global_store_dwordx2 v[6:7], v[4:5], off offset:2560
	s_waitcnt lgkmcnt(1)
	v_pk_add_f32 v[4:5], v[96:97], 0 op_sel_hi:[1, 0]
	v_pk_add_f32 v[6:7], v[98:99], 0 op_sel_hi:[1, 0]
	v_cvt_pk_bf16_f32 v4, v4, v5
	v_cvt_pk_bf16_f32 v5, v6, v7
	v_add_u32_e32 v6, 0x60, v8
	v_mad_i64_i32 v[6:7], s[0:1], v6, s50, v[2:3]
	global_store_dwordx2 v[6:7], v[4:5], off offset:2560
	v_add_u32_e32 v0, 0x70, v8
	v_mad_i64_i32 v[2:3], s[0:1], v0, s50, v[2:3]
	s_waitcnt lgkmcnt(0)
	v_pk_add_f32 v[4:5], v[100:101], 0 op_sel_hi:[1, 0]
	v_pk_add_f32 v[6:7], v[102:103], 0 op_sel_hi:[1, 0]
	v_cvt_pk_bf16_f32 v4, v4, v5
	v_cvt_pk_bf16_f32 v5, v6, v7
	global_store_dwordx2 v[2:3], v[4:5], off offset:2560
	v_cndmask_b32_e64 v3, 0, 1, s[6:7]
	v_ashrrev_i32_e32 v0, 2, v18
	v_and_b32_e32 v2, -8, v0
	v_cmp_ne_u32_e64 s[0:1], 1, v3
	v_ashrrev_i32_e32 v3, 31, v2
	s_cbranch_vccnz .LBB0_2203
	v_readlane_b32 s6, v254, 7
	v_readlane_b32 s7, v254, 8
	s_nop 1
	v_lshl_add_u64 v[4:5], v[2:3], 2, s[6:7]
	global_load_dword v10, v[4:5], off offset:256

; #define TIDX (tid_launder())
; DI unsigned pack2(float a, float b) { hwf2 v = {a, b}; hwbf2 r = __builtin_convertvector(v, hwbf2); return __builtin_bit_cast(unsigned, r); }
; DI float siluf(float x) { return x * __builtin_amdgcn_rcpf(1.f + __expf(-x)); }
; DI void epi_store64(const float* Ct, int cb, const float* rn, int grp, const float* gain, bool silu, const float* bias,
;                     bf16_t* dst, size_t ldd, int dcol0, int m0, int Mmax) {
;   const int tid = TIDX, c = (tid & 15) * 4;
;   float4 gv = make_float4(1.f, 1.f, 1.f, 1.f), bv = make_float4(0.f, 0.f, 0.f, 0.f);
;   if (rn) gv = *(const float4*)(gain + c);
;   if (bias) bv = *(const float4*)(bias + c);
; #pragma unroll
;   for (int q = 0; q < 8; ++q) {
;     const int row = (tid >> 4) + 16 * q;
;     float4 v = *(const float4*)(Ct + row * 132 + cb + c);
;     v.x += bv.x; v.y += bv.y; v.z += bv.z; v.w += bv.w;
;     if (rn) { const float sc = rn[row * 2 + grp]; v.x *= sc * gv.x; v.y *= sc * gv.y; v.z *= sc * gv.z; v.w *= sc * gv.w; }
;     if (silu) { v.x = siluf(v.x); v.y = siluf(v.y); v.z = siluf(v.z); v.w = siluf(v.w); }
;     uint2 o; o.x = pack2(v.x, v.y); o.y = pack2(v.z, v.w);
;     *(uint2*)(dst + (size_t)(m0 + row) * ldd + dcol0 + c) = o;
;   }
; }
.LBB0_2228:
	s_and_b64 vcc, exec, s[4:5]
	s_cbranch_vccz .LBB0_2230
	v_mov_b32_e32 v0, v230
	v_readlane_b32 s16, v252, 57
	s_lshl_b32 s0, s34, 1
	v_lshlrev_b32_e32 v2, 2, v0
	v_readlane_b32 s26, v253, 3
	v_and_b32_e32 v4, 60, v2
	v_readlane_b32 s27, v253, 4
	s_add_u32 s0, s26, s0
	v_ashrrev_i32_e32 v8, 4, v0
	s_addc_u32 s1, s27, 0
	v_lshlrev_b32_e32 v0, 1, v4
	v_lshl_add_u64 v[2:3], s[0:1], 0, v[0:1]
	v_mul_lo_u32 v0, v8, s79
	v_lshl_add_u32 v0, v4, 2, v0
	ds_read_b128 v[72:75], v0
	ds_read_b128 v[76:79], v0 offset:8448
	ds_read_b128 v[80:83], v0 offset:16896
	ds_read_b128 v[84:87], v0 offset:25344
	ds_read_b128 v[88:91], v0 offset:33792
	ds_read_b128 v[92:95], v0 offset:42240
	ds_read_b128 v[96:99], v0 offset:50688
	ds_read_b128 v[100:103], v0 offset:59136
	v_add_u32_e32 v8, s13, v8
	s_movk_i32 s3, 0xc00
	v_readlane_b32 s17, v252, 58
	v_readlane_b32 s18, v252, 59
	s_waitcnt lgkmcnt(7)
	v_pk_add_f32 v[4:5], v[72:73], 0 op_sel_hi:[1, 0]
	v_pk_add_f32 v[6:7], v[74:75], 0 op_sel_hi:[1, 0]
	v_cvt_pk_bf16_f32 v4, v4, v5
	v_cvt_pk_bf16_f32 v5, v6, v7
	v_mad_i64_i32 v[6:7], s[4:5], v8, s3, v[2:3]
	global_store_dwordx2 v[6:7], v[4:5], off offset:-3328
	v_readlane_b32 s19, v252, 60
	v_readlane_b32 s20, v252, 61
	v_readlane_b32 s21, v252, 62
	v_readlane_b32 s22, v252, 63
	s_waitcnt lgkmcnt(6)
	v_pk_add_f32 v[4:5], v[76:77], 0 op_sel_hi:[1, 0]
	v_pk_add_f32 v[6:7], v[78:79], 0 op_sel_hi:[1, 0]
	v_cvt_pk_bf16_f32 v4, v4, v5
	v_cvt_pk_bf16_f32 v5, v6, v7
	v_add_u32_e32 v6, 16, v8
	v_mad_i64_i32 v[6:7], s[4:5], v6, s3, v[2:3]
	global_store_dwordx2 v[6:7], v[4:5], off offset:-3328
	v_readlane_b32 s23, v253, 0
	v_readlane_b32 s24, v253, 1
	v_readlane_b32 s25, v253, 2
	v_readlane_b32 s28, v253, 5
	s_waitcnt lgkmcnt(5)
	v_pk_add_f32 v[4:5], v[80:81], 0 op_sel_hi:[1, 0]
	v_pk_add_f32 v[6:7], v[82:83], 0 op_sel_hi:[1, 0]
	v_cvt_pk_bf16_f32 v4, v4, v5
	v_cvt_pk_bf16_f32 v5, v6, v7
	v_add_u32_e32 v6, 32, v8
	v_mad_i64_i32 v[6:7], s[4:5], v6, s3, v[2:3]
	global_store_dwordx2 v[6:7], v[4:5], off offset:-3328
	v_readlane_b32 s29, v253, 6
	v_readlane_b32 s30, v253, 7
	v_readlane_b32 s31, v253, 8
	s_mov_b64 s[6:7], 0
	s_waitcnt lgkmcnt(4)
	v_pk_add_f32 v[4:5], v[84:85], 0 op_sel_hi:[1, 0]
	v_pk_add_f32 v[6:7], v[86:87], 0 op_sel_hi:[1, 0]
	v_cvt_pk_bf16_f32 v4, v4, v5
	v_cvt_pk_bf16_f32 v5, v6, v7
	v_add_u32_e32 v6, 48, v8
	v_mad_i64_i32 v[6:7], s[4:5], v6, s3, v[2:3]
	global_store_dwordx2 v[6:7], v[4:5], off offset:-3328
	s_waitcnt lgkmcnt(3)
	v_pk_add_f32 v[4:5], v[88:89], 0 op_sel_hi:[1, 0]
	v_pk_add_f32 v[6:7], v[90:91], 0 op_sel_hi:[1, 0]
	v_cvt_pk_bf16_f32 v4, v4, v5
	v_cvt_pk_bf16_f32 v5, v6, v7
	v_add_u32_e32 v6, 64, v8
	v_mad_i64_i32 v[6:7], s[4:5], v6, s3, v[2:3]
	global_store_dwordx2 v[6:7], v[4:5], off offset:-3328
	s_waitcnt lgkmcnt(2)
	v_pk_add_f32 v[4:5], v[92:93], 0 op_sel_hi:[1, 0]
	v_pk_add_f32 v[6:7], v[94:95], 0 op_sel_hi:[1, 0]
	v_cvt_pk_bf16_f32 v4, v4, v5
	v_cvt_pk_bf16_f32 v5, v6, v7
	v_add_u32_e32 v6, 0x50, v8
	v_mad_i64_i32 v[6:7], s[4:5], v6, s3, v[2:3]
	global_store_dwordx2 v[6:7], v[4:5], off offset:-3328
	s_waitcnt lgkmcnt(1)
	v_pk_add_f32 v[4:5], v[96:97], 0 op_sel_hi:[1, 0]
	v_pk_add_f32 v[6:7], v[98:99], 0 op_sel_hi:[1, 0]
	v_cvt_pk_bf16_f32 v4, v4, v5
	v_cvt_pk_bf16_f32 v5, v6, v7
	v_add_u32_e32 v6, 0x60, v8
	v_mad_i64_i32 v[6:7], s[4:5], v6, s3, v[2:3]
	global_store_dwordx2 v[6:7], v[4:5], off offset:-3328
	v_add_u32_e32 v0, 0x70, v8
	v_mad_i64_i32 v[2:3], s[4:5], v0, s3, v[2:3]
	v_mov_b32_e32 v0, v230
	s_waitcnt lgkmcnt(0)
	v_pk_add_f32 v[4:5], v[100:101], 0 op_sel_hi:[1, 0]
	v_pk_add_f32 v[6:7], v[102:103], 0 op_sel_hi:[1, 0]
	v_cvt_pk_bf16_f32 v4, v4, v5
	v_cvt_pk_bf16_f32 v5, v6, v7
	global_store_dwordx2 v[2:3], v[4:5], off offset:-3328
	s_nop 0
	v_lshlrev_b32_e32 v2, 2, v0
	v_and_b32_e32 v4, 60, v2
	v_ashrrev_i32_e32 v8, 4, v0
	v_lshlrev_b32_e32 v0, 1, v4
	v_lshl_add_u64 v[2:3], s[0:1], 0, v[0:1]
	v_mul_lo_u32 v0, v8, s79
	v_lshl_add_u32 v0, v4, 2, v0
	ds_read_b128 v[72:75], v0 offset:256
	ds_read_b128 v[76:79], v0 offset:8704
	ds_read_b128 v[80:83], v0 offset:17152
	ds_read_b128 v[84:87], v0 offset:25600
	ds_read_b128 v[88:91], v0 offset:34048
	ds_read_b128 v[92:95], v0 offset:42496
	ds_read_b128 v[96:99], v0 offset:50944
	ds_read_b128 v[100:103], v0 offset:59392
	v_add_u32_e32 v8, s13, v8
	s_waitcnt lgkmcnt(7)
	v_pk_add_f32 v[4:5], v[72:73], 0 op_sel_hi:[1, 0]
	v_pk_add_f32 v[6:7], v[74:75], 0 op_sel_hi:[1, 0]
	v_cvt_pk_bf16_f32 v4, v4, v5
	v_cvt_pk_bf16_f32 v5, v6, v7
	v_mad_i64_i32 v[6:7], s[0:1], v8, s3, v[2:3]
	global_store_dwordx2 v[6:7], v[4:5], off offset:-3200
	s_waitcnt lgkmcnt(6)
	v_pk_add_f32 v[4:5], v[76:77], 0 op_sel_hi:[1, 0]
	v_pk_add_f32 v[6:7], v[78:79], 0 op_sel_hi:[1, 0]
	v_cvt_pk_bf16_f32 v4, v4, v5
	v_cvt_pk_bf16_f32 v5, v6, v7
	v_add_u32_e32 v6, 16, v8
	v_mad_i64_i32 v[6:7], s[0:1], v6, s3, v[2:3]
	global_store_dwordx2 v[6:7], v[4:5], off offset:-3200
	s_waitcnt lgkmcnt(5)
	v_pk_add_f32 v[4:5], v[80:81], 0 op_sel_hi:[1, 0]
	v_pk_add_f32 v[6:7], v[82:83], 0 op_sel_hi:[1, 0]
	v_cvt_pk_bf16_f32 v4, v4, v5
	v_cvt_pk_bf16_f32 v5, v6, v7
	v_add_u32_e32 v6, 32, v8
	v_mad_i64_i32 v[6:7], s[0:1], v6, s3, v[2:3]
	global_store_dwordx2 v[6:7], v[4:5], off offset:-3200
	s_waitcnt lgkmcnt(4)
	v_pk_add_f32 v[4:5], v[84:85], 0 op_sel_hi:[1, 0]
	v_pk_add_f32 v[6:7], v[86:87], 0 op_sel_hi:[1, 0]
	v_cvt_pk_bf16_f32 v4, v4, v5
	v_cvt_pk_bf16_f32 v5, v6, v7
	v_add_u32_e32 v6, 48, v8
	v_mad_i64_i32 v[6:7], s[0:1], v6, s3, v[2:3]
	global_store_dwordx2 v[6:7], v[4:5], off offset:-3200
	s_waitcnt lgkmcnt(3)
	v_pk_add_f32 v[4:5], v[88:89], 0 op_sel_hi:[1, 0]
	v_pk_add_f32 v[6:7], v[90:91], 0 op_sel_hi:[1, 0]
	v_cvt_pk_bf16_f32 v4, v4, v5
	v_cvt_pk_bf16_f32 v5, v6, v7
	v_add_u32_e32 v6, 64, v8
	v_mad_i64_i32 v[6:7], s[0:1], v6, s3, v[2:3]
	global_store_dwordx2 v[6:7], v[4:5], off offset:-3200
	s_waitcnt lgkmcnt(2)
	v_pk_add_f32 v[4:5], v[92:93], 0 op_sel_hi:[1, 0]
	v_pk_add_f32 v[6:7], v[94:95], 0 op_sel_hi:[1, 0]
	v_cvt_pk_bf16_f32 v4, v4, v5
	v_cvt_pk_bf16_f32 v5, v6, v7
	v_add_u32_e32 v6, 0x50, v8
	v_mad_i64_i32 v[6:7], s[0:1], v6, s3, v[2:3]
	global_store_dwordx2 v[6:7], v[4:5], off offset:-3200
	s_waitcnt lgkmcnt(1)
	v_pk_add_f32 v[4:5], v[96:97], 0 op_sel_hi:[1, 0]
	v_pk_add_f32 v[6:7], v[98:99], 0 op_sel_hi:[1, 0]
	v_cvt_pk_bf16_f32 v4, v4, v5
	v_cvt_pk_bf16_f32 v5, v6, v7
	v_add_u32_e32 v6, 0x60, v8
	v_mad_i64_i32 v[6:7], s[0:1], v6, s3, v[2:3]
	global_store_dwordx2 v[6:7], v[4:5], off offset:-3200
	v_add_u32_e32 v0, 0x70, v8
	v_mad_i64_i32 v[2:3], s[0:1], v0, s3, v[2:3]
	s_waitcnt lgkmcnt(0)
	v_pk_add_f32 v[4:5], v[100:101], 0 op_sel_hi:[1, 0]
	v_pk_add_f32 v[6:7], v[102:103], 0 op_sel_hi:[1, 0]
	v_cvt_pk_bf16_f32 v4, v4, v5
	v_cvt_pk_bf16_f32 v5, v6, v7
	global_store_dwordx2 v[2:3], v[4:5], off offset:-3200
; #define TIDX (tid_launder())
; DI unsigned pack2(float a, float b) { hwf2 v = {a, b}; hwbf2 r = __builtin_convertvector(v, hwbf2); return __builtin_bit_cast(unsigned, r); }
; DI float siluf(float x) { return x * __builtin_amdgcn_rcpf(1.f + __expf(-x)); }
; DI void epi_store64(const float* Ct, int cb, const float* rn, int grp, const float* gain, bool silu, const float* bias,
;                     bf16_t* dst, size_t ldd, int dcol0, int m0, int Mmax) {
;   const int tid = TIDX, c = (tid & 15) * 4;
;   float4 gv = make_float4(1.f, 1.f, 1.f, 1.f), bv = make_float4(0.f, 0.f, 0.f, 0.f);
;   if (rn) gv = *(const float4*)(gain + c);
;   if (bias) bv = *(const float4*)(bias + c);
; #pragma unroll
;   for (int q = 0; q < 8; ++q) {
;     const int row = (tid >> 4) + 16 * q;
;     float4 v = *(const float4*)(Ct + row * 132 + cb + c);
;     v.x += bv.x; v.y += bv.y; v.z += bv.z; v.w += bv.w;
;     if (rn) { const float sc = rn[row * 2 + grp]; v.x *= sc * gv.x; v.y *= sc * gv.y; v.z *= sc * gv.z; v.w *= sc * gv.w; }
;     if (silu) { v.x = siluf(v.x); v.y = siluf(v.y); v.z = siluf(v.z); v.w = siluf(v.w); }
;     uint2 o; o.x = pack2(v.x, v.y); o.y = pack2(v.z, v.w);
;     *(uint2*)(dst + (size_t)(m0 + row) * ldd + dcol0 + c) = o;
;   }
; }
; DI void epi_storeKF(const float* Ct, int cb, const float* rn, int grp, const float* gain, bf16_t* dst) {
;   const int slot = TIDX, r = slot & 31, d0 = (slot >> 5) * 8;
;   float gq[8];
; #pragma unroll
;   for (int j = 0; j < 8; ++j) gq[j] = rn ? gain[d0 + j] : 1.f;
; #pragma unroll
;   for (int kt4 = 0; kt4 < 4; ++kt4) {
;     const int row = kt4 * 32 + r;
;     float v[8];
;     {
;       const float4 va = *(const float4*)(Ct + row * 132 + cb + d0), vb = *(const float4*)(Ct + row * 132 + cb + d0 + 4);
;       v[0] = va.x; v[1] = va.y; v[2] = va.z; v[3] = va.w; v[4] = vb.x; v[5] = vb.y; v[6] = vb.z; v[7] = vb.w;
;     }
;     if (rn) { const float sc = rn[row * 2 + grp];
; #pragma unroll
;       for (int j = 0; j < 8; ++j) v[j] *= sc * gq[j]; }
;     uint4 o; o.x = pack2(v[0], v[1]); o.y = pack2(v[2], v[3]); o.z = pack2(v[4], v[5]); o.w = pack2(v[6], v[7]);
;     *(uint4*)(dst + kt4 * 2048 + slot * 8) = o;
;   }
; }
.LBB0_2230:
	s_andn2_b64 vcc, exec, s[6:7]
	s_cbranch_vccnz .LBB0_2232
	s_ashr_i32 s3, s2, 31
	s_ashr_i32 s0, s14, 5
	v_readlane_b32 s16, v253, 11
	s_ashr_i32 s1, s0, 31
	s_lshl_b64 s[2:3], s[2:3], 18
	v_readlane_b32 s18, v253, 13
	v_readlane_b32 s19, v253, 14
	s_add_u32 s2, s18, s2
	s_addc_u32 s3, s19, s3
	s_lshl_b64 s[0:1], s[0:1], 12
	v_mov_b32_e32 v0, v230
	s_add_u32 s0, s2, s0
	s_addc_u32 s1, s3, s1
	v_and_b32_e32 v4, 31, v0
	v_and_b32_e32 v5, 0xffffffe0, v0
	v_lshlrev_b32_e32 v2, 3, v0
	v_ashrrev_i32_e32 v3, 31, v2
	v_mad_u32_u24 v0, v4, s79, v5
	s_waitcnt vmcnt(4)
	v_lshl_add_u64 v[10:11], v[2:3], 1, s[0:1]
	ds_read_b128 v[2:5], v0
	ds_read_b128 v[6:9], v0 offset:16
	v_add_co_u32_e32 v12, vcc, s80, v10
	v_readlane_b32 s17, v253, 12
	s_waitcnt lgkmcnt(1)
	v_cvt_pk_bf16_f32 v2, v2, v3
	v_cvt_pk_bf16_f32 v3, v4, v5
	s_waitcnt lgkmcnt(0)
	v_cvt_pk_bf16_f32 v4, v6, v7
	v_cvt_pk_bf16_f32 v5, v8, v9
	global_store_dwordx4 v[10:11], v[2:5], off
	ds_read_b128 v[2:5], v0 offset:16896
	ds_read_b128 v[6:9], v0 offset:16912
	v_addc_co_u32_e32 v13, vcc, 0, v11, vcc
	v_readlane_b32 s20, v253, 15
	s_waitcnt lgkmcnt(1)
	v_cvt_pk_bf16_f32 v2, v2, v3
	v_cvt_pk_bf16_f32 v3, v4, v5
	s_waitcnt lgkmcnt(0)
	v_cvt_pk_bf16_f32 v4, v6, v7
	v_cvt_pk_bf16_f32 v5, v8, v9
	global_store_dwordx4 v[12:13], v[2:5], off offset:-4096
	ds_read_b128 v[2:5], v0 offset:33792
	ds_read_b128 v[6:9], v0 offset:33808
	v_readlane_b32 s21, v253, 16
	v_readlane_b32 s22, v253, 17
	v_readlane_b32 s23, v253, 18
	s_waitcnt lgkmcnt(1)
	v_cvt_pk_bf16_f32 v2, v2, v3
	v_cvt_pk_bf16_f32 v3, v4, v5
	s_waitcnt lgkmcnt(0)
	v_cvt_pk_bf16_f32 v4, v6, v7
	v_cvt_pk_bf16_f32 v5, v8, v9
	global_store_dwordx4 v[12:13], v[2:5], off
	ds_read_b128 v[2:5], v0 offset:50688
	ds_read_b128 v[6:9], v0 offset:50704
	v_mov_b32_e32 v0, v230
	v_readlane_b32 s24, v253, 19
	v_readlane_b32 s25, v253, 20
	s_waitcnt lgkmcnt(1)
	v_cvt_pk_bf16_f32 v2, v2, v3
	v_cvt_pk_bf16_f32 v3, v4, v5
	s_waitcnt lgkmcnt(0)
	v_cvt_pk_bf16_f32 v4, v6, v7
	v_add_co_u32_e32 v6, vcc, s81, v10
	v_cvt_pk_bf16_f32 v5, v8, v9
	s_nop 0
	v_addc_co_u32_e32 v7, vcc, 0, v11, vcc
	v_readlane_b32 s26, v253, 21
	v_readlane_b32 s27, v253, 22
	v_readlane_b32 s28, v253, 23
	v_readlane_b32 s29, v253, 24
	v_readlane_b32 s30, v253, 25
	v_readlane_b32 s31, v253, 26
	global_store_dwordx4 v[6:7], v[2:5], off
	v_readlane_b32 s16, v252, 57
	v_ashrrev_i32_e32 v8, 4, v0
	v_lshlrev_b32_e32 v2, 2, v0
	v_and_b32_e32 v4, 60, v2
	v_lshlrev_b32_e32 v0, 1, v4
	v_readlane_b32 s24, v253, 1
	v_readlane_b32 s25, v253, 2
	v_readlane_b32 s17, v252, 58
	v_readlane_b32 s18, v252, 59
	v_lshl_add_u64 v[2:3], s[24:25], 0, v[0:1]
	v_mul_lo_u32 v0, v8, s79
	v_lshl_add_u32 v0, v4, 2, v0
	ds_read_b128 v[72:75], v0 offset:256
	ds_read_b128 v[76:79], v0 offset:8704
	ds_read_b128 v[80:83], v0 offset:17152
	ds_read_b128 v[84:87], v0 offset:25600
	ds_read_b128 v[88:91], v0 offset:34048
	ds_read_b128 v[92:95], v0 offset:42496
	ds_read_b128 v[96:99], v0 offset:50944
	ds_read_b128 v[100:103], v0 offset:59392
	v_add_u32_e32 v8, s13, v8
	v_readlane_b32 s19, v252, 60
	v_readlane_b32 s20, v252, 61
	v_readlane_b32 s21, v252, 62
	s_waitcnt lgkmcnt(7)
	v_pk_add_f32 v[4:5], v[72:73], 0 op_sel_hi:[1, 0]
	v_pk_add_f32 v[6:7], v[74:75], 0 op_sel_hi:[1, 0]
	v_cvt_pk_bf16_f32 v4, v4, v5
	v_cvt_pk_bf16_f32 v5, v6, v7
	v_mad_i64_i32 v[6:7], s[0:1], v8, s50, v[2:3]
	global_store_dwordx2 v[6:7], v[4:5], off offset:2432
	v_readlane_b32 s22, v252, 63
	v_readlane_b32 s23, v253, 0
	v_readlane_b32 s26, v253, 3
	v_readlane_b32 s27, v253, 4
	s_waitcnt lgkmcnt(6)
	v_pk_add_f32 v[4:5], v[76:77], 0 op_sel_hi:[1, 0]
	v_pk_add_f32 v[6:7], v[78:79], 0 op_sel_hi:[1, 0]
	v_cvt_pk_bf16_f32 v4, v4, v5
	v_cvt_pk_bf16_f32 v5, v6, v7
	v_add_u32_e32 v6, 16, v8
	v_mad_i64_i32 v[6:7], s[0:1], v6, s50, v[2:3]
	global_store_dwordx2 v[6:7], v[4:5], off offset:2432
	v_readlane_b32 s28, v253, 5
	v_readlane_b32 s29, v253, 6
	v_readlane_b32 s30, v253, 7
	v_readlane_b32 s31, v253, 8
	s_waitcnt lgkmcnt(5)
	v_pk_add_f32 v[4:5], v[80:81], 0 op_sel_hi:[1, 0]
	v_pk_add_f32 v[6:7], v[82:83], 0 op_sel_hi:[1, 0]
	v_cvt_pk_bf16_f32 v4, v4, v5
	v_cvt_pk_bf16_f32 v5, v6, v7
	v_add_u32_e32 v6, 32, v8
	v_mad_i64_i32 v[6:7], s[0:1], v6, s50, v[2:3]
	global_store_dwordx2 v[6:7], v[4:5], off offset:2432
	s_waitcnt lgkmcnt(4)
	v_pk_add_f32 v[4:5], v[84:85], 0 op_sel_hi:[1, 0]
	v_pk_add_f32 v[6:7], v[86:87], 0 op_sel_hi:[1, 0]
	v_cvt_pk_bf16_f32 v4, v4, v5
	v_cvt_pk_bf16_f32 v5, v6, v7
	v_add_u32_e32 v6, 48, v8
	v_mad_i64_i32 v[6:7], s[0:1], v6, s50, v[2:3]
	global_store_dwordx2 v[6:7], v[4:5], off offset:2432
	s_waitcnt lgkmcnt(3)
	v_pk_add_f32 v[4:5], v[88:89], 0 op_sel_hi:[1, 0]
	v_pk_add_f32 v[6:7], v[90:91], 0 op_sel_hi:[1, 0]
	v_cvt_pk_bf16_f32 v4, v4, v5
	v_cvt_pk_bf16_f32 v5, v6, v7
	v_add_u32_e32 v6, 64, v8
	v_mad_i64_i32 v[6:7], s[0:1], v6, s50, v[2:3]
	global_store_dwordx2 v[6:7], v[4:5], off offset:2432
	s_waitcnt lgkmcnt(2)
	v_pk_add_f32 v[4:5], v[92:93], 0 op_sel_hi:[1, 0]
	v_pk_add_f32 v[6:7], v[94:95], 0 op_sel_hi:[1, 0]
	v_cvt_pk_bf16_f32 v4, v4, v5
	v_cvt_pk_bf16_f32 v5, v6, v7
	v_add_u32_e32 v6, 0x50, v8
	v_mad_i64_i32 v[6:7], s[0:1], v6, s50, v[2:3]
	global_store_dwordx2 v[6:7], v[4:5], off offset:2432
	s_waitcnt lgkmcnt(1)
	v_pk_add_f32 v[4:5], v[96:97], 0 op_sel_hi:[1, 0]
	v_pk_add_f32 v[6:7], v[98:99], 0 op_sel_hi:[1, 0]
	v_cvt_pk_bf16_f32 v4, v4, v5
	v_cvt_pk_bf16_f32 v5, v6, v7
	v_add_u32_e32 v6, 0x60, v8
	v_mad_i64_i32 v[6:7], s[0:1], v6, s50, v[2:3]
	global_store_dwordx2 v[6:7], v[4:5], off offset:2432
	v_add_u32_e32 v0, 0x70, v8
	v_mad_i64_i32 v[2:3], s[0:1], v0, s50, v[2:3]
	s_waitcnt lgkmcnt(0)
	v_pk_add_f32 v[4:5], v[100:101], 0 op_sel_hi:[1, 0]
	v_pk_add_f32 v[6:7], v[102:103], 0 op_sel_hi:[1, 0]
	v_cvt_pk_bf16_f32 v4, v4, v5
	v_cvt_pk_bf16_f32 v5, v6, v7
	global_store_dwordx2 v[2:3], v[4:5], off offset:2432

; #define TIDX (tid_launder())
; DI unsigned pack2(float a, float b) { hwf2 v = {a, b}; hwbf2 r = __builtin_convertvector(v, hwbf2); return __builtin_bit_cast(unsigned, r); }
; DI float siluf(float x) { return x * __builtin_amdgcn_rcpf(1.f + __expf(-x)); }
; DI void epi_store64(const float* Ct, int cb, const float* rn, int grp, const float* gain, bool silu, const float* bias,
;                     bf16_t* dst, size_t ldd, int dcol0, int m0, int Mmax) {
;   const int tid = TIDX, c = (tid & 15) * 4;
;   float4 gv = make_float4(1.f, 1.f, 1.f, 1.f), bv = make_float4(0.f, 0.f, 0.f, 0.f);
;   if (rn) gv = *(const float4*)(gain + c);
;   if (bias) bv = *(const float4*)(bias + c);
; #pragma unroll
;   for (int q = 0; q < 8; ++q) {
;     const int row = (tid >> 4) + 16 * q;
;     float4 v = *(const float4*)(Ct + row * 132 + cb + c);
;     v.x += bv.x; v.y += bv.y; v.z += bv.z; v.w += bv.w;
;     if (rn) { const float sc = rn[row * 2 + grp]; v.x *= sc * gv.x; v.y *= sc * gv.y; v.z *= sc * gv.z; v.w *= sc * gv.w; }
;     if (silu) { v.x = siluf(v.x); v.y = siluf(v.y); v.z = siluf(v.z); v.w = siluf(v.w); }
;     uint2 o; o.x = pack2(v.x, v.y); o.y = pack2(v.z, v.w);
;     *(uint2*)(dst + (size_t)(m0 + row) * ldd + dcol0 + c) = o;
;   }
; }
.LBB0_2233:
	s_and_b64 vcc, exec, s[0:1]
	s_cbranch_vccz .LBB0_2235
	v_mov_b32_e32 v0, v230
	v_readlane_b32 s16, v252, 57
	s_lshl_b32 s0, s34, 1
	v_lshlrev_b32_e32 v2, 2, v0
	v_readlane_b32 s24, v253, 1
	v_and_b32_e32 v4, 60, v2
	v_readlane_b32 s25, v253, 2
	s_add_u32 s0, s24, s0
	v_ashrrev_i32_e32 v8, 4, v0
	s_addc_u32 s1, s25, 0
	v_lshlrev_b32_e32 v0, 1, v4
	v_lshl_add_u64 v[2:3], s[0:1], 0, v[0:1]
	v_mul_lo_u32 v0, v8, s79
	v_lshl_add_u32 v0, v4, 2, v0
	ds_read_b128 v[72:75], v0
	ds_read_b128 v[76:79], v0 offset:8448
	ds_read_b128 v[80:83], v0 offset:16896
	ds_read_b128 v[84:87], v0 offset:25344
	ds_read_b128 v[88:91], v0 offset:33792
	ds_read_b128 v[92:95], v0 offset:42240
	ds_read_b128 v[96:99], v0 offset:50688
	ds_read_b128 v[100:103], v0 offset:59136
	v_add_u32_e32 v8, s13, v8
	v_readlane_b32 s17, v252, 58
	v_readlane_b32 s18, v252, 59
	v_readlane_b32 s19, v252, 60
	s_waitcnt lgkmcnt(7)
	v_pk_add_f32 v[4:5], v[72:73], 0 op_sel_hi:[1, 0]
	v_pk_add_f32 v[6:7], v[74:75], 0 op_sel_hi:[1, 0]
	v_cvt_pk_bf16_f32 v4, v4, v5
	v_cvt_pk_bf16_f32 v5, v6, v7
	v_mad_i64_i32 v[6:7], s[2:3], v8, s50, v[2:3]
	global_store_dwordx2 v[6:7], v[4:5], off
	v_readlane_b32 s20, v252, 61
	v_readlane_b32 s21, v252, 62
	v_readlane_b32 s22, v252, 63
	v_readlane_b32 s23, v253, 0
	s_waitcnt lgkmcnt(6)
	v_pk_add_f32 v[4:5], v[76:77], 0 op_sel_hi:[1, 0]
	v_pk_add_f32 v[6:7], v[78:79], 0 op_sel_hi:[1, 0]
	v_cvt_pk_bf16_f32 v4, v4, v5
	v_cvt_pk_bf16_f32 v5, v6, v7
	v_add_u32_e32 v6, 16, v8
	v_mad_i64_i32 v[6:7], s[2:3], v6, s50, v[2:3]
	global_store_dwordx2 v[6:7], v[4:5], off
	v_readlane_b32 s26, v253, 3
	v_readlane_b32 s27, v253, 4
	v_readlane_b32 s28, v253, 5
	v_readlane_b32 s29, v253, 6
	s_waitcnt lgkmcnt(5)
	v_pk_add_f32 v[4:5], v[80:81], 0 op_sel_hi:[1, 0]
	v_pk_add_f32 v[6:7], v[82:83], 0 op_sel_hi:[1, 0]
	v_cvt_pk_bf16_f32 v4, v4, v5
	v_cvt_pk_bf16_f32 v5, v6, v7
	v_add_u32_e32 v6, 32, v8
	v_mad_i64_i32 v[6:7], s[2:3], v6, s50, v[2:3]
	global_store_dwordx2 v[6:7], v[4:5], off
	v_readlane_b32 s30, v253, 7
	v_readlane_b32 s31, v253, 8
	s_waitcnt lgkmcnt(4)
	v_pk_add_f32 v[4:5], v[84:85], 0 op_sel_hi:[1, 0]
	v_pk_add_f32 v[6:7], v[86:87], 0 op_sel_hi:[1, 0]
	v_cvt_pk_bf16_f32 v4, v4, v5
	v_cvt_pk_bf16_f32 v5, v6, v7
	v_add_u32_e32 v6, 48, v8
	v_mad_i64_i32 v[6:7], s[2:3], v6, s50, v[2:3]
	global_store_dwordx2 v[6:7], v[4:5], off
	s_waitcnt lgkmcnt(3)
	v_pk_add_f32 v[4:5], v[88:89], 0 op_sel_hi:[1, 0]
	v_pk_add_f32 v[6:7], v[90:91], 0 op_sel_hi:[1, 0]
	v_cvt_pk_bf16_f32 v4, v4, v5
	v_cvt_pk_bf16_f32 v5, v6, v7
	v_add_u32_e32 v6, 64, v8
	v_mad_i64_i32 v[6:7], s[2:3], v6, s50, v[2:3]
	global_store_dwordx2 v[6:7], v[4:5], off
	s_waitcnt lgkmcnt(2)
	v_pk_add_f32 v[4:5], v[92:93], 0 op_sel_hi:[1, 0]
	v_pk_add_f32 v[6:7], v[94:95], 0 op_sel_hi:[1, 0]
	v_cvt_pk_bf16_f32 v4, v4, v5
	v_cvt_pk_bf16_f32 v5, v6, v7
	v_add_u32_e32 v6, 0x50, v8
	v_mad_i64_i32 v[6:7], s[2:3], v6, s50, v[2:3]
	global_store_dwordx2 v[6:7], v[4:5], off
	s_waitcnt lgkmcnt(1)
	v_pk_add_f32 v[4:5], v[96:97], 0 op_sel_hi:[1, 0]
	v_pk_add_f32 v[6:7], v[98:99], 0 op_sel_hi:[1, 0]
	v_cvt_pk_bf16_f32 v4, v4, v5
	v_cvt_pk_bf16_f32 v5, v6, v7
	v_add_u32_e32 v6, 0x60, v8
	v_mad_i64_i32 v[6:7], s[2:3], v6, s50, v[2:3]
	global_store_dwordx2 v[6:7], v[4:5], off
	v_add_u32_e32 v0, 0x70, v8
	v_mad_i64_i32 v[2:3], s[2:3], v0, s50, v[2:3]
	v_mov_b32_e32 v0, v230
	s_waitcnt lgkmcnt(0)
	v_pk_add_f32 v[4:5], v[100:101], 0 op_sel_hi:[1, 0]
	v_pk_add_f32 v[6:7], v[102:103], 0 op_sel_hi:[1, 0]
	v_cvt_pk_bf16_f32 v4, v4, v5
	v_cvt_pk_bf16_f32 v5, v6, v7
	global_store_dwordx2 v[2:3], v[4:5], off
	s_nop 0
	v_lshlrev_b32_e32 v2, 2, v0
	v_and_b32_e32 v4, 60, v2
	v_ashrrev_i32_e32 v8, 4, v0
	v_lshlrev_b32_e32 v0, 1, v4
	v_lshl_add_u64 v[2:3], s[0:1], 0, v[0:1]
	v_mul_lo_u32 v0, v8, s79
	v_lshl_add_u32 v0, v4, 2, v0
	ds_read_b128 v[72:75], v0 offset:256
	ds_read_b128 v[76:79], v0 offset:8704
	ds_read_b128 v[80:83], v0 offset:17152
	ds_read_b128 v[84:87], v0 offset:25600
	ds_read_b128 v[88:91], v0 offset:34048
	ds_read_b128 v[92:95], v0 offset:42496
	ds_read_b128 v[96:99], v0 offset:50944
	ds_read_b128 v[100:103], v0 offset:59392
	v_add_u32_e32 v8, s13, v8
	s_waitcnt lgkmcnt(7)
	v_pk_add_f32 v[4:5], v[72:73], 0 op_sel_hi:[1, 0]
	v_pk_add_f32 v[6:7], v[74:75], 0 op_sel_hi:[1, 0]
	v_cvt_pk_bf16_f32 v4, v4, v5
	v_cvt_pk_bf16_f32 v5, v6, v7
	v_mad_i64_i32 v[6:7], s[0:1], v8, s50, v[2:3]
	global_store_dwordx2 v[6:7], v[4:5], off offset:128
	s_waitcnt lgkmcnt(6)
	v_pk_add_f32 v[4:5], v[76:77], 0 op_sel_hi:[1, 0]
	v_pk_add_f32 v[6:7], v[78:79], 0 op_sel_hi:[1, 0]
	v_cvt_pk_bf16_f32 v4, v4, v5
	v_cvt_pk_bf16_f32 v5, v6, v7
	v_add_u32_e32 v6, 16, v8
	v_mad_i64_i32 v[6:7], s[0:1], v6, s50, v[2:3]
	global_store_dwordx2 v[6:7], v[4:5], off offset:128
	s_waitcnt lgkmcnt(5)
	v_pk_add_f32 v[4:5], v[80:81], 0 op_sel_hi:[1, 0]
	v_pk_add_f32 v[6:7], v[82:83], 0 op_sel_hi:[1, 0]
	v_cvt_pk_bf16_f32 v4, v4, v5
	v_cvt_pk_bf16_f32 v5, v6, v7
	v_add_u32_e32 v6, 32, v8
	v_mad_i64_i32 v[6:7], s[0:1], v6, s50, v[2:3]
	global_store_dwordx2 v[6:7], v[4:5], off offset:128
	s_waitcnt lgkmcnt(4)
	v_pk_add_f32 v[4:5], v[84:85], 0 op_sel_hi:[1, 0]
	v_pk_add_f32 v[6:7], v[86:87], 0 op_sel_hi:[1, 0]
	v_cvt_pk_bf16_f32 v4, v4, v5
	v_cvt_pk_bf16_f32 v5, v6, v7
	v_add_u32_e32 v6, 48, v8
	v_mad_i64_i32 v[6:7], s[0:1], v6, s50, v[2:3]
	global_store_dwordx2 v[6:7], v[4:5], off offset:128
	s_waitcnt lgkmcnt(3)
	v_pk_add_f32 v[4:5], v[88:89], 0 op_sel_hi:[1, 0]
	v_pk_add_f32 v[6:7], v[90:91], 0 op_sel_hi:[1, 0]
	v_cvt_pk_bf16_f32 v4, v4, v5
	v_cvt_pk_bf16_f32 v5, v6, v7
	v_add_u32_e32 v6, 64, v8
	v_mad_i64_i32 v[6:7], s[0:1], v6, s50, v[2:3]
	global_store_dwordx2 v[6:7], v[4:5], off offset:128
	s_waitcnt lgkmcnt(2)
	v_pk_add_f32 v[4:5], v[92:93], 0 op_sel_hi:[1, 0]
	v_pk_add_f32 v[6:7], v[94:95], 0 op_sel_hi:[1, 0]
	v_cvt_pk_bf16_f32 v4, v4, v5
	v_cvt_pk_bf16_f32 v5, v6, v7
	v_add_u32_e32 v6, 0x50, v8
	v_mad_i64_i32 v[6:7], s[0:1], v6, s50, v[2:3]
	global_store_dwordx2 v[6:7], v[4:5], off offset:128
	s_waitcnt lgkmcnt(1)
	v_pk_add_f32 v[4:5], v[96:97], 0 op_sel_hi:[1, 0]
	v_pk_add_f32 v[6:7], v[98:99], 0 op_sel_hi:[1, 0]
	v_cvt_pk_bf16_f32 v4, v4, v5
	v_cvt_pk_bf16_f32 v5, v6, v7
	v_add_u32_e32 v6, 0x60, v8
	v_mad_i64_i32 v[6:7], s[0:1], v6, s50, v[2:3]
	global_store_dwordx2 v[6:7], v[4:5], off offset:128
	v_add_u32_e32 v0, 0x70, v8
	v_mad_i64_i32 v[2:3], s[0:1], v0, s50, v[2:3]
	s_waitcnt lgkmcnt(0)
	v_pk_add_f32 v[4:5], v[100:101], 0 op_sel_hi:[1, 0]
	v_pk_add_f32 v[6:7], v[102:103], 0 op_sel_hi:[1, 0]
	v_cvt_pk_bf16_f32 v4, v4, v5
	v_cvt_pk_bf16_f32 v5, v6, v7
	global_store_dwordx2 v[2:3], v[4:5], off offset:128
